# v17 plus: redundant second s_waitcnt lgkmcnt(0) at the head of each K-loop MFMA segment removed (24 sites)
# speedup vs baseline: 1.0101x; 1.0101x over previous
; #define PG8_STAGE(bufoff, gbase, voff) do { _Pragma("unroll") for (int _i = 0; _i < 2; ++_i) \
;         __builtin_amdgcn_global_load_lds((const unsigned*)((const char*)(gbase) + (voff)[_i]), (LAS unsigned*)(lds + (bufoff) + ldsw + _i * 8192), 16, 0, 0); } while (0)
; #define PG8_LDA(dst, b, h) do { _Pragma("unroll") for (int m = 0; m < 4; ++m) _Pragma("unroll") for (int k = 0; k < 2; ++k) dst[m][k] = *(const LAS bf16x8*)(lds + PG8_SA(b, h) + aoff + m * 2048 + k * 1024); } while (0)
; #define PG8_LDB(dst, b, h) do { _Pragma("unroll") for (int n = 0; n < 2; ++n) _Pragma("unroll") for (int k = 0; k < 2; ++k) dst[n][k] = *(const LAS bf16x8*)(lds + PG8_SB(b, h) + boff + n * 2048 + k * 1024); } while (0)
; #define PG8_MMA(ai, bj, At, Bt) do { __builtin_amdgcn_s_setprio(1); _Pragma("unroll") for (int m = 0; m < 4; ++m) _Pragma("unroll") for (int n = 0; n < 2; ++n) _Pragma("unroll") for (int k = 0; k < 2; ++k) \
;         acc[ai][bj][m][n] = __builtin_amdgcn_mfma_f32_16x16x32_bf16(Bt[n][k], At[m][k], acc[ai][bj][m][n], 0, 0, 0); __builtin_amdgcn_s_setprio(0); } while (0)
; #define PG8_WAIT_V(n) asm volatile("s_waitcnt vmcnt(" #n ")" ::: "memory")
; #define PG8_WAIT_L(n) asm volatile("s_waitcnt lgkmcnt(" #n ")" ::: "memory")
; #define PG8_BAR __builtin_amdgcn_s_barrier()
; #define PG8_SCHED __builtin_amdgcn_sched_barrier(0)
; template <class Epi, class Sched>
; __device__ __forceinline__ void gemm_phase(LAS unsigned char* lds, const Gemm g, const Sched& S, const Epi& E) {
;     ...
;             PG8_LDB(B0, 0, 0); PG8_SCHED; PG8_LDA(At, 0, 0); PG8_STAGE(PG8_SA(1, 1), a1 + hstep, voffA);
;             PG8_WAIT_L(8); PG8_BAR; PG8_WAIT_L(0); PG8_MMA(0, 0, At, B0); PG8_BAR; PG8_SCHED;
;             PG8_LDB(B1, 0, 1); PG8_STAGE(PG8_SB(0, 0), b2, voffB);
;             PG8_BAR; PG8_WAIT_L(0); PG8_MMA(0, 1, At, B1); PG8_BAR;
;             PG8_LDA(At, 0, 1); PG8_STAGE(PG8_SA(0, 0), a2, voffA);
;             PG8_BAR; PG8_WAIT_L(0); PG8_MMA(1, 0, At, B0); PG8_BAR; PG8_SCHED;
;             PG8_STAGE(PG8_SB(0, 1), b2 + hstep, voffB);
;             PG8_WAIT_V(6); PG8_BAR; PG8_MMA(1, 1, At, B1); PG8_BAR;
.LBB0_125:
	s_add_u32 s20, s16, 0xfff80080
	s_addc_u32 s21, s17, -1
	s_add_i32 s45, 0, 0x10000
	ds_read_b128 v[138:141], v129
	ds_read_b128 v[160:163], v129 offset:1024
	ds_read_b128 v[164:167], v129 offset:2048
	ds_read_b128 v[168:171], v129 offset:3072
	s_cmp_eq_u32 s44, 28
	s_cselect_b32 s23, s7, s21
	s_cselect_b32 s22, s40, s20
	s_cselect_b32 s21, s5, s43
	s_cselect_b32 s20, s41, s42
	s_add_i32 m0, s30, 0xc000
	ds_read_b128 v[172:175], v145
	ds_read_b128 v[200:203], v145 offset:1024
	ds_read_b128 v[204:207], v145 offset:2048
	ds_read_b128 v[208:211], v145 offset:3072
	ds_read_b128 v[212:215], v145 offset:4096
	ds_read_b128 v[216:219], v145 offset:5120
	ds_read_b128 v[220:223], v145 offset:6144
	ds_read_b128 v[224:227], v145 offset:7168
	global_load_lds_dwordx4 v134, s[16:17]
	s_add_i32 m0, s30, 0xe000
	s_nop 0
	global_load_lds_dwordx4 v136, s[16:17]
	s_waitcnt lgkmcnt(8)
	s_barrier
	s_waitcnt lgkmcnt(0)
	v_mfma_f32_16x16x32_bf16 v[124:127], v[138:141], v[172:175], v[124:127]
	v_mfma_f32_16x16x32_bf16 v[120:123], v[164:167], v[172:175], v[120:123]
	v_mfma_f32_16x16x32_bf16 v[116:119], v[138:141], v[204:207], v[116:119]
	v_mfma_f32_16x16x32_bf16 v[108:111], v[164:167], v[204:207], v[108:111]
	v_mfma_f32_16x16x32_bf16 v[100:103], v[138:141], v[212:215], v[100:103]
	v_mfma_f32_16x16x32_bf16 v[92:95], v[164:167], v[212:215], v[92:95]
	v_mfma_f32_16x16x32_bf16 v[84:87], v[138:141], v[220:223], v[84:87]
	v_mfma_f32_16x16x32_bf16 v[76:79], v[164:167], v[220:223], v[76:79]
	v_mfma_f32_16x16x32_bf16 v[124:127], v[160:163], v[200:203], v[124:127]
	v_mfma_f32_16x16x32_bf16 v[120:123], v[168:171], v[200:203], v[120:123]
	v_mfma_f32_16x16x32_bf16 v[116:119], v[160:163], v[208:211], v[116:119]
	v_mfma_f32_16x16x32_bf16 v[108:111], v[168:171], v[208:211], v[108:111]
	v_mfma_f32_16x16x32_bf16 v[100:103], v[160:163], v[216:219], v[100:103]
	v_mfma_f32_16x16x32_bf16 v[92:95], v[168:171], v[216:219], v[92:95]
	v_mfma_f32_16x16x32_bf16 v[84:87], v[160:163], v[224:227], v[84:87]
	v_mfma_f32_16x16x32_bf16 v[76:79], v[168:171], v[224:227], v[76:79]
	s_barrier
	s_add_i32 s48, 0, 0x14000
	s_add_i32 s45, s45, s29
	ds_read_b128 v[228:231], v129 offset:16384
	ds_read_b128 v[232:235], v129 offset:17408
	ds_read_b128 v[236:239], v129 offset:18432
	ds_read_b128 v[240:243], v129 offset:19456
	s_add_u32 s84, s20, 0x80
	s_addc_u32 s85, s21, 0
	s_mov_b32 m0, s45
	s_nop 0
	global_load_lds_dwordx4 v148, s[20:21]
	s_add_i32 m0, s45, 0x2000
	s_nop 0
	global_load_lds_dwordx4 v128, s[20:21]
	s_barrier
	s_waitcnt lgkmcnt(0)
	v_mfma_f32_16x16x32_bf16 v[112:115], v[228:231], v[172:175], v[112:115]
	v_mfma_f32_16x16x32_bf16 v[104:107], v[236:239], v[172:175], v[104:107]
	v_mfma_f32_16x16x32_bf16 v[96:99], v[228:231], v[204:207], v[96:99]
	v_mfma_f32_16x16x32_bf16 v[88:91], v[236:239], v[204:207], v[88:91]
	v_mfma_f32_16x16x32_bf16 v[80:83], v[228:231], v[212:215], v[80:83]
	v_mfma_f32_16x16x32_bf16 v[72:75], v[236:239], v[212:215], v[72:75]
	v_mfma_f32_16x16x32_bf16 v[68:71], v[228:231], v[220:223], v[68:71]
	v_mfma_f32_16x16x32_bf16 v[64:67], v[236:239], v[220:223], v[64:67]
	v_mfma_f32_16x16x32_bf16 v[112:115], v[232:235], v[200:203], v[112:115]
	v_mfma_f32_16x16x32_bf16 v[104:107], v[240:243], v[200:203], v[104:107]
	v_mfma_f32_16x16x32_bf16 v[96:99], v[232:235], v[208:211], v[96:99]
	v_mfma_f32_16x16x32_bf16 v[88:91], v[240:243], v[208:211], v[88:91]
	v_mfma_f32_16x16x32_bf16 v[80:83], v[232:235], v[216:219], v[80:83]
	v_mfma_f32_16x16x32_bf16 v[72:75], v[240:243], v[216:219], v[72:75]
	v_mfma_f32_16x16x32_bf16 v[68:71], v[232:235], v[224:227], v[68:71]
	v_mfma_f32_16x16x32_bf16 v[64:67], v[240:243], v[224:227], v[64:67]
	s_mov_b32 m0, s30
	s_add_u32 s86, s22, 0x80
	s_addc_u32 s87, s23, 0
	s_barrier
	ds_read_b128 v[172:175], v145 offset:16384
	ds_read_b128 v[200:203], v145 offset:17408
	ds_read_b128 v[204:207], v145 offset:18432
	ds_read_b128 v[208:211], v145 offset:19456
	ds_read_b128 v[212:215], v145 offset:20480
	ds_read_b128 v[216:219], v145 offset:21504
	ds_read_b128 v[220:223], v145 offset:22528
	ds_read_b128 v[224:227], v145 offset:23552
	global_load_lds_dwordx4 v132, s[22:23]
	s_mov_b32 m0, s31
	s_nop 0
	global_load_lds_dwordx4 v130, s[22:23]
	s_barrier
	s_waitcnt lgkmcnt(0)
	v_mfma_f32_16x16x32_bf16 v[60:63], v[138:141], v[172:175], v[60:63]
	v_mfma_f32_16x16x32_bf16 v[56:59], v[164:167], v[172:175], v[56:59]
	v_mfma_f32_16x16x32_bf16 v[52:55], v[138:141], v[204:207], v[52:55]
	v_mfma_f32_16x16x32_bf16 v[44:47], v[164:167], v[204:207], v[44:47]
	v_mfma_f32_16x16x32_bf16 v[36:39], v[138:141], v[212:215], v[36:39]
	v_mfma_f32_16x16x32_bf16 v[28:31], v[164:167], v[212:215], v[28:31]
	v_mfma_f32_16x16x32_bf16 v[20:23], v[138:141], v[220:223], v[20:23]
	v_mfma_f32_16x16x32_bf16 v[12:15], v[164:167], v[220:223], v[12:15]
	v_mfma_f32_16x16x32_bf16 v[60:63], v[160:163], v[200:203], v[60:63]
	v_mfma_f32_16x16x32_bf16 v[56:59], v[168:171], v[200:203], v[56:59]
	v_mfma_f32_16x16x32_bf16 v[52:55], v[160:163], v[208:211], v[52:55]
	v_mfma_f32_16x16x32_bf16 v[44:47], v[168:171], v[208:211], v[44:47]
	v_mfma_f32_16x16x32_bf16 v[36:39], v[160:163], v[216:219], v[36:39]
	v_mfma_f32_16x16x32_bf16 v[28:31], v[168:171], v[216:219], v[28:31]
	v_mfma_f32_16x16x32_bf16 v[20:23], v[160:163], v[224:227], v[20:23]
	v_mfma_f32_16x16x32_bf16 v[12:15], v[168:171], v[224:227], v[12:15]
	s_barrier
	s_add_u32 s46, s20, 0x80000
	s_addc_u32 s47, s21, 0
	s_add_i32 s45, s48, s29
	s_mov_b32 m0, s45
	s_nop 0
	global_load_lds_dwordx4 v148, s[46:47]
	s_add_i32 m0, s45, 0x2000
	s_nop 0
	global_load_lds_dwordx4 v128, s[46:47]
	s_waitcnt vmcnt(6)
	s_barrier
; #define PG8_STAGE(bufoff, gbase, voff) do { _Pragma("unroll") for (int _i = 0; _i < 2; ++_i) \
;         __builtin_amdgcn_global_load_lds((const unsigned*)((const char*)(gbase) + (voff)[_i]), (LAS unsigned*)(lds + (bufoff) + ldsw + _i * 8192), 16, 0, 0); } while (0)
; #define PG8_LDA(dst, b, h) do { _Pragma("unroll") for (int m = 0; m < 4; ++m) _Pragma("unroll") for (int k = 0; k < 2; ++k) dst[m][k] = *(const LAS bf16x8*)(lds + PG8_SA(b, h) + aoff + m * 2048 + k * 1024); } while (0)
; #define PG8_LDB(dst, b, h) do { _Pragma("unroll") for (int n = 0; n < 2; ++n) _Pragma("unroll") for (int k = 0; k < 2; ++k) dst[n][k] = *(const LAS bf16x8*)(lds + PG8_SB(b, h) + boff + n * 2048 + k * 1024); } while (0)
; #define PG8_MMA(ai, bj, At, Bt) do { __builtin_amdgcn_s_setprio(1); _Pragma("unroll") for (int m = 0; m < 4; ++m) _Pragma("unroll") for (int n = 0; n < 2; ++n) _Pragma("unroll") for (int k = 0; k < 2; ++k) \
;         acc[ai][bj][m][n] = __builtin_amdgcn_mfma_f32_16x16x32_bf16(Bt[n][k], At[m][k], acc[ai][bj][m][n], 0, 0, 0); __builtin_amdgcn_s_setprio(0); } while (0)
; #define PG8_WAIT_V(n) asm volatile("s_waitcnt vmcnt(" #n ")" ::: "memory")
; #define PG8_WAIT_L(n) asm volatile("s_waitcnt lgkmcnt(" #n ")" ::: "memory")
; #define PG8_BAR __builtin_amdgcn_s_barrier()
; #define PG8_SCHED __builtin_amdgcn_sched_barrier(0)
; template <class Epi, class Sched>
; __device__ __forceinline__ void gemm_phase(LAS unsigned char* lds, const Gemm g, const Sched& S, const Epi& E) {
;     ...
;             PG8_WAIT_V(6); PG8_BAR; PG8_MMA(1, 1, At, B1); PG8_BAR;
;             PG8_LDB(B0, 1, 0); PG8_SCHED; PG8_LDA(At, 1, 0); PG8_STAGE(PG8_SA(0, 1), a2 + hstep, voffA);
;             PG8_WAIT_L(8); PG8_BAR; PG8_WAIT_L(0); PG8_MMA(0, 0, At, B0); PG8_BAR; PG8_SCHED;
;             PG8_LDB(B1, 1, 1); PG8_STAGE(PG8_SB(1, 0), b3, voffB);
;             PG8_BAR; PG8_WAIT_L(0); PG8_MMA(0, 1, At, B1); PG8_BAR;
;             PG8_LDA(At, 1, 1); PG8_STAGE(PG8_SA(1, 0), a3, voffA);
;             PG8_BAR; PG8_WAIT_L(0); PG8_MMA(1, 0, At, B0); PG8_BAR; PG8_SCHED;
	v_mfma_f32_16x16x32_bf16 v[48:51], v[228:231], v[172:175], v[48:51]
	v_mfma_f32_16x16x32_bf16 v[40:43], v[236:239], v[172:175], v[40:43]
	v_mfma_f32_16x16x32_bf16 v[32:35], v[228:231], v[204:207], v[32:35]
	v_mfma_f32_16x16x32_bf16 v[24:27], v[236:239], v[204:207], v[24:27]
	v_mfma_f32_16x16x32_bf16 v[16:19], v[228:231], v[212:215], v[16:19]
	v_mfma_f32_16x16x32_bf16 v[8:11], v[236:239], v[212:215], v[8:11]
	v_mfma_f32_16x16x32_bf16 v[4:7], v[228:231], v[220:223], v[4:7]
	v_mfma_f32_16x16x32_bf16 v[0:3], v[236:239], v[220:223], v[0:3]
	v_mfma_f32_16x16x32_bf16 v[48:51], v[232:235], v[200:203], v[48:51]
	v_mfma_f32_16x16x32_bf16 v[40:43], v[240:243], v[200:203], v[40:43]
	v_mfma_f32_16x16x32_bf16 v[32:35], v[232:235], v[208:211], v[32:35]
	v_mfma_f32_16x16x32_bf16 v[24:27], v[240:243], v[208:211], v[24:27]
	v_mfma_f32_16x16x32_bf16 v[16:19], v[232:235], v[216:219], v[16:19]
	v_mfma_f32_16x16x32_bf16 v[8:11], v[240:243], v[216:219], v[8:11]
	v_mfma_f32_16x16x32_bf16 v[4:7], v[232:235], v[224:227], v[4:7]
	v_mfma_f32_16x16x32_bf16 v[0:3], v[240:243], v[224:227], v[0:3]
	s_add_i32 s45, 0, 0x18000
	s_barrier
	ds_read_b128 v[138:141], v129 offset:32768
	ds_read_b128 v[160:163], v129 offset:33792
	ds_read_b128 v[164:167], v129 offset:34816
	ds_read_b128 v[168:171], v129 offset:35840
	s_add_u32 s22, s22, 0x80000
	s_addc_u32 s23, s23, 0
	s_mov_b32 m0, s33
	ds_read_b128 v[172:175], v145 offset:32768
	ds_read_b128 v[200:203], v145 offset:33792
	ds_read_b128 v[204:207], v145 offset:34816
	ds_read_b128 v[208:211], v145 offset:35840
	ds_read_b128 v[212:215], v145 offset:36864
	ds_read_b128 v[216:219], v145 offset:37888
	ds_read_b128 v[220:223], v145 offset:38912
	ds_read_b128 v[224:227], v145 offset:39936
	global_load_lds_dwordx4 v132, s[22:23]
	s_mov_b32 m0, s34
	s_nop 0
	global_load_lds_dwordx4 v130, s[22:23]
	s_waitcnt lgkmcnt(8)
	s_barrier
	s_waitcnt lgkmcnt(0)
	v_mfma_f32_16x16x32_bf16 v[124:127], v[138:141], v[172:175], v[124:127]
	v_mfma_f32_16x16x32_bf16 v[120:123], v[164:167], v[172:175], v[120:123]
	v_mfma_f32_16x16x32_bf16 v[116:119], v[138:141], v[204:207], v[116:119]
	v_mfma_f32_16x16x32_bf16 v[108:111], v[164:167], v[204:207], v[108:111]
	v_mfma_f32_16x16x32_bf16 v[100:103], v[138:141], v[212:215], v[100:103]
	v_mfma_f32_16x16x32_bf16 v[92:95], v[164:167], v[212:215], v[92:95]
	v_mfma_f32_16x16x32_bf16 v[84:87], v[138:141], v[220:223], v[84:87]
	v_mfma_f32_16x16x32_bf16 v[76:79], v[164:167], v[220:223], v[76:79]
	v_mfma_f32_16x16x32_bf16 v[124:127], v[160:163], v[200:203], v[124:127]
	v_mfma_f32_16x16x32_bf16 v[120:123], v[168:171], v[200:203], v[120:123]
	v_mfma_f32_16x16x32_bf16 v[116:119], v[160:163], v[208:211], v[116:119]
	v_mfma_f32_16x16x32_bf16 v[108:111], v[168:171], v[208:211], v[108:111]
	v_mfma_f32_16x16x32_bf16 v[100:103], v[160:163], v[216:219], v[100:103]
	v_mfma_f32_16x16x32_bf16 v[92:95], v[168:171], v[216:219], v[92:95]
	v_mfma_f32_16x16x32_bf16 v[84:87], v[160:163], v[224:227], v[84:87]
	v_mfma_f32_16x16x32_bf16 v[76:79], v[168:171], v[224:227], v[76:79]
	s_barrier
	s_add_i32 s22, 0, 0x1c000
	s_add_i32 s23, s45, s29
	s_mov_b32 m0, s23
	ds_read_b128 v[228:231], v129 offset:49152
	ds_read_b128 v[232:235], v129 offset:50176
	ds_read_b128 v[236:239], v129 offset:51200
	ds_read_b128 v[240:243], v129 offset:52224
	global_load_lds_dwordx4 v148, s[84:85]
	s_add_i32 m0, s23, 0x2000
	s_nop 0
	global_load_lds_dwordx4 v128, s[84:85]
	s_barrier
	s_waitcnt lgkmcnt(0)
	v_mfma_f32_16x16x32_bf16 v[112:115], v[228:231], v[172:175], v[112:115]
	v_mfma_f32_16x16x32_bf16 v[104:107], v[236:239], v[172:175], v[104:107]
	v_mfma_f32_16x16x32_bf16 v[96:99], v[228:231], v[204:207], v[96:99]
	v_mfma_f32_16x16x32_bf16 v[88:91], v[236:239], v[204:207], v[88:91]
	v_mfma_f32_16x16x32_bf16 v[80:83], v[228:231], v[212:215], v[80:83]
	v_mfma_f32_16x16x32_bf16 v[72:75], v[236:239], v[212:215], v[72:75]
	v_mfma_f32_16x16x32_bf16 v[68:71], v[228:231], v[220:223], v[68:71]
	v_mfma_f32_16x16x32_bf16 v[64:67], v[236:239], v[220:223], v[64:67]
	v_mfma_f32_16x16x32_bf16 v[112:115], v[232:235], v[200:203], v[112:115]
	v_mfma_f32_16x16x32_bf16 v[104:107], v[240:243], v[200:203], v[104:107]
	v_mfma_f32_16x16x32_bf16 v[96:99], v[232:235], v[208:211], v[96:99]
	v_mfma_f32_16x16x32_bf16 v[88:91], v[240:243], v[208:211], v[88:91]
	v_mfma_f32_16x16x32_bf16 v[80:83], v[232:235], v[216:219], v[80:83]
	v_mfma_f32_16x16x32_bf16 v[72:75], v[240:243], v[216:219], v[72:75]
	v_mfma_f32_16x16x32_bf16 v[68:71], v[232:235], v[224:227], v[68:71]
	v_mfma_f32_16x16x32_bf16 v[64:67], v[240:243], v[224:227], v[64:67]
	s_mov_b32 m0, s35
	s_barrier
	ds_read_b128 v[172:175], v145 offset:49152
	ds_read_b128 v[200:203], v145 offset:50176
	ds_read_b128 v[204:207], v145 offset:51200
	ds_read_b128 v[208:211], v145 offset:52224
	ds_read_b128 v[212:215], v145 offset:53248
	ds_read_b128 v[216:219], v145 offset:54272
	ds_read_b128 v[220:223], v145 offset:55296
	ds_read_b128 v[224:227], v145 offset:56320
	global_load_lds_dwordx4 v132, s[86:87]
	s_mov_b32 m0, s36
	s_nop 0
	global_load_lds_dwordx4 v130, s[86:87]
	s_barrier
	s_waitcnt lgkmcnt(0)
	v_mfma_f32_16x16x32_bf16 v[60:63], v[138:141], v[172:175], v[60:63]
	v_mfma_f32_16x16x32_bf16 v[56:59], v[164:167], v[172:175], v[56:59]
	v_mfma_f32_16x16x32_bf16 v[52:55], v[138:141], v[204:207], v[52:55]
	v_mfma_f32_16x16x32_bf16 v[44:47], v[164:167], v[204:207], v[44:47]
	v_mfma_f32_16x16x32_bf16 v[36:39], v[138:141], v[212:215], v[36:39]
	v_mfma_f32_16x16x32_bf16 v[28:31], v[164:167], v[212:215], v[28:31]
	v_mfma_f32_16x16x32_bf16 v[20:23], v[138:141], v[220:223], v[20:23]
	v_mfma_f32_16x16x32_bf16 v[12:15], v[164:167], v[220:223], v[12:15]
	v_mfma_f32_16x16x32_bf16 v[60:63], v[160:163], v[200:203], v[60:63]
	v_mfma_f32_16x16x32_bf16 v[56:59], v[168:171], v[200:203], v[56:59]
	v_mfma_f32_16x16x32_bf16 v[52:55], v[160:163], v[208:211], v[52:55]
	v_mfma_f32_16x16x32_bf16 v[44:47], v[168:171], v[208:211], v[44:47]
	v_mfma_f32_16x16x32_bf16 v[36:39], v[160:163], v[216:219], v[36:39]
	v_mfma_f32_16x16x32_bf16 v[28:31], v[168:171], v[216:219], v[28:31]
	v_mfma_f32_16x16x32_bf16 v[20:23], v[160:163], v[224:227], v[20:23]
	v_mfma_f32_16x16x32_bf16 v[12:15], v[168:171], v[224:227], v[12:15]
	s_barrier
; __device__ __forceinline__ unsigned cvt_pk_bf16(float lo, float hi) { unsigned r; asm("v_cvt_pk_bf16_f32 %0, %1, %2" : "=v"(r) : "v"(lo), "v"(hi)); return r; }
; #define PG8_STAGE(bufoff, gbase, voff) do { _Pragma("unroll") for (int _i = 0; _i < 2; ++_i) \
;         __builtin_amdgcn_global_load_lds((const unsigned*)((const char*)(gbase) + (voff)[_i]), (LAS unsigned*)(lds + (bufoff) + ldsw + _i * 8192), 16, 0, 0); } while (0)
; #define PG8_MMA(ai, bj, At, Bt) do { __builtin_amdgcn_s_setprio(1); _Pragma("unroll") for (int m = 0; m < 4; ++m) _Pragma("unroll") for (int n = 0; n < 2; ++n) _Pragma("unroll") for (int k = 0; k < 2; ++k) \
;         acc[ai][bj][m][n] = __builtin_amdgcn_mfma_f32_16x16x32_bf16(Bt[n][k], At[m][k], acc[ai][bj][m][n], 0, 0, 0); __builtin_amdgcn_s_setprio(0); } while (0)
; #define PG8_WAIT_V(n) asm volatile("s_waitcnt vmcnt(" #n ")" ::: "memory")
; #define PG8_WAIT_L(n) asm volatile("s_waitcnt lgkmcnt(" #n ")" ::: "memory")
; #define PG8_BAR __builtin_amdgcn_s_barrier()
; #define PG8_SCHED __builtin_amdgcn_sched_barrier(0)
;     __device__ __forceinline__ void operator()(const f32x4 (&acc)[2][2][4][2], const Unit& u, int wr, int wc, int fr, int fq) const {
;         const int row0 = u.pm * BM + wr * 64 + fr, col0 = u.pn * BM + wc * 32 + 8 * fq;
; #pragma unroll
;         for (int ai = 0; ai < 2; ++ai)
; #pragma unroll
;             for (int m = 0; m < 4; ++m) { bf16_t* rowp = O + (size_t)(row0 + ai * HALF + m * 16) * ldc + col0;
; #pragma unroll
;                 for (int bj = 0; bj < 2; ++bj) { const f32x4 v0 = acc[ai][bj][m][0], v1 = acc[ai][bj][m][1];
;                     u32x4 w; w.x = cvt_pk_bf16(v0[0], v0[1]); w.y = cvt_pk_bf16(v0[2], v0[3]); w.z = cvt_pk_bf16(v1[0], v1[1]); w.w = cvt_pk_bf16(v1[2], v1[3]);
;                     *(u32x4*)(rowp + bj * HALF) = w; } }
; template <class Epi, class Sched>
; __device__ __forceinline__ void gemm_phase(LAS unsigned char* lds, const Gemm g, const Sched& S, const Epi& E) {
;     ...
;             PG8_BAR; PG8_WAIT_L(0); PG8_MMA(1, 0, At, B0); PG8_BAR; PG8_SCHED;
;             PG8_STAGE(PG8_SB(1, 1), b3 + hstep, voffB);
;             PG8_WAIT_V(6); PG8_BAR; PG8_MMA(1, 1, At, B1); PG8_BAR;
	s_add_u32 s20, s20, 0x80080
	s_addc_u32 s21, s21, 0
	s_add_i32 s22, s22, s29
	s_mov_b32 m0, s22
	s_nop 0
	global_load_lds_dwordx4 v148, s[20:21]
	s_add_i32 m0, s22, 0x2000
	s_nop 0
	global_load_lds_dwordx4 v128, s[20:21]
	s_waitcnt vmcnt(6)
	s_barrier
	v_mfma_f32_16x16x32_bf16 v[48:51], v[228:231], v[172:175], v[48:51]
	v_mfma_f32_16x16x32_bf16 v[40:43], v[236:239], v[172:175], v[40:43]
	v_mfma_f32_16x16x32_bf16 v[32:35], v[228:231], v[204:207], v[32:35]
	v_mfma_f32_16x16x32_bf16 v[24:27], v[236:239], v[204:207], v[24:27]
	v_mfma_f32_16x16x32_bf16 v[16:19], v[228:231], v[212:215], v[16:19]
	v_mfma_f32_16x16x32_bf16 v[8:11], v[236:239], v[212:215], v[8:11]
	v_mfma_f32_16x16x32_bf16 v[4:7], v[228:231], v[220:223], v[4:7]
	v_mfma_f32_16x16x32_bf16 v[0:3], v[236:239], v[220:223], v[0:3]
	v_mfma_f32_16x16x32_bf16 v[48:51], v[232:235], v[200:203], v[48:51]
	v_mfma_f32_16x16x32_bf16 v[40:43], v[240:243], v[200:203], v[40:43]
	v_mfma_f32_16x16x32_bf16 v[32:35], v[232:235], v[208:211], v[32:35]
	v_mfma_f32_16x16x32_bf16 v[24:27], v[240:243], v[208:211], v[24:27]
	v_mfma_f32_16x16x32_bf16 v[16:19], v[232:235], v[216:219], v[16:19]
	v_mfma_f32_16x16x32_bf16 v[8:11], v[240:243], v[216:219], v[8:11]
	v_mfma_f32_16x16x32_bf16 v[4:7], v[232:235], v[224:227], v[4:7]
	v_mfma_f32_16x16x32_bf16 v[0:3], v[240:243], v[224:227], v[0:3]
	s_add_i32 s44, s44, 2
	s_add_u32 s16, s16, 0x100
	s_addc_u32 s17, s17, 0
	s_add_u32 s42, s42, 0x100
	s_addc_u32 s43, s43, 0
	s_cmp_gt_u32 s44, 29
	s_barrier
	s_cbranch_scc0 .LBB0_125
	v_lshl_add_u32 v160, s39, 8, v142
	v_lshl_or_b32 v140, s38, 8, v144
	v_ashrrev_i32_e32 v141, 31, v140
	v_mov_b64_e32 v[138:139], s[2:3]
	v_cvt_pk_bf16_f32 v68, v68, v69
	v_cvt_pk_bf16_f32 v69, v70, v71
	v_cvt_pk_bf16_f32 v70, v64, v65
	v_add_u32_e32 v64, 0x80, v160
	v_mad_i64_i32 v[146:147], s[16:17], v160, s56, v[138:139]
	v_lshlrev_b64 v[140:141], 1, v[140:141]
	v_cvt_pk_bf16_f32 v112, v112, v113
	v_cvt_pk_bf16_f32 v113, v114, v115
	v_cvt_pk_bf16_f32 v114, v104, v105
	v_or_b32_e32 v104, 16, v160
	v_mad_i64_i32 v[64:65], s[16:17], v64, s56, v[138:139]
	v_cvt_pk_bf16_f32 v48, v48, v49
	v_cvt_pk_bf16_f32 v49, v50, v51
	v_cvt_pk_bf16_f32 v50, v40, v41
	v_add_u32_e32 v40, 0x90, v160
	v_lshl_add_u64 v[146:147], v[146:147], 0, v[140:141]
	v_mad_i64_i32 v[104:105], s[16:17], v104, s56, v[138:139]
	v_cvt_pk_bf16_f32 v96, v96, v97
	v_cvt_pk_bf16_f32 v97, v98, v99
	v_cvt_pk_bf16_f32 v98, v88, v89
	v_or_b32_e32 v88, 32, v160
	v_lshl_add_u64 v[64:65], v[64:65], 0, v[140:141]
	v_mad_i64_i32 v[40:41], s[16:17], v40, s56, v[138:139]
	v_cvt_pk_bf16_f32 v32, v32, v33
	v_cvt_pk_bf16_f32 v33, v34, v35
	v_cvt_pk_bf16_f32 v34, v24, v25
	v_add_u32_e32 v24, 0xa0, v160
	v_cvt_pk_bf16_f32 v115, v106, v107
	global_store_dwordx4 v[146:147], v[112:115], off offset:256
	v_mad_i64_i32 v[88:89], s[16:17], v88, s56, v[138:139]
	s_nop 0
	v_lshl_add_u64 v[112:113], v[104:105], 0, v[140:141]
	v_cvt_pk_bf16_f32 v80, v80, v81
	v_cvt_pk_bf16_f32 v81, v82, v83
	v_cvt_pk_bf16_f32 v82, v72, v73
	v_or_b32_e32 v72, 48, v160
	v_cvt_pk_bf16_f32 v51, v42, v43
	global_store_dwordx4 v[64:65], v[48:51], off offset:256
	v_mad_i64_i32 v[24:25], s[16:17], v24, s56, v[138:139]
	s_nop 0
	v_lshl_add_u64 v[48:49], v[40:41], 0, v[140:141]
	v_cvt_pk_bf16_f32 v16, v16, v17
	v_cvt_pk_bf16_f32 v17, v18, v19
	v_cvt_pk_bf16_f32 v18, v8, v9
	v_add_u32_e32 v8, 0xb0, v160
	v_cvt_pk_bf16_f32 v99, v90, v91
	global_store_dwordx4 v[112:113], v[96:99], off offset:256
	v_mad_i64_i32 v[72:73], s[16:17], v72, s56, v[138:139]
	s_nop 0
	v_lshl_add_u64 v[96:97], v[88:89], 0, v[140:141]
	v_cvt_pk_bf16_f32 v35, v26, v27
	global_store_dwordx4 v[48:49], v[32:35], off offset:256
	v_mad_i64_i32 v[8:9], s[16:17], v8, s56, v[138:139]
	s_nop 0
	v_lshl_add_u64 v[32:33], v[24:25], 0, v[140:141]
	v_cvt_pk_bf16_f32 v83, v74, v75
	global_store_dwordx4 v[96:97], v[80:83], off offset:256
	v_cvt_pk_bf16_f32 v19, v10, v11
	global_store_dwordx4 v[32:33], v[16:19], off offset:256
	s_and_b64 vcc, exec, s[0:1]
	v_lshl_add_u64 v[80:81], v[72:73], 0, v[140:141]
	v_lshl_add_u64 v[16:17], v[8:9], 0, v[140:141]
	s_mov_b32 s38, s4
	s_mov_b32 s39, s6
	s_mov_b64 s[20:21], s[14:15]
	s_mov_b64 s[16:17], s[12:13]
	v_cvt_pk_bf16_f32 v124, v124, v125
	v_cvt_pk_bf16_f32 v125, v126, v127
	v_cvt_pk_bf16_f32 v126, v120, v121
	v_cvt_pk_bf16_f32 v127, v122, v123
	global_store_dwordx4 v[146:147], v[124:127], off
	v_cvt_pk_bf16_f32 v104, v116, v117
	v_cvt_pk_bf16_f32 v105, v118, v119
	v_cvt_pk_bf16_f32 v106, v108, v109
	v_cvt_pk_bf16_f32 v107, v110, v111
	global_store_dwordx4 v[112:113], v[104:107], off
	v_cvt_pk_bf16_f32 v88, v100, v101
	v_cvt_pk_bf16_f32 v89, v102, v103
	v_cvt_pk_bf16_f32 v90, v92, v93
	v_cvt_pk_bf16_f32 v91, v94, v95
	global_store_dwordx4 v[96:97], v[88:91], off
	v_cvt_pk_bf16_f32 v72, v84, v85
	v_cvt_pk_bf16_f32 v73, v86, v87
	v_cvt_pk_bf16_f32 v74, v76, v77
	v_cvt_pk_bf16_f32 v75, v78, v79
	global_store_dwordx4 v[80:81], v[72:75], off
	v_cvt_pk_bf16_f32 v71, v66, v67
	global_store_dwordx4 v[80:81], v[68:71], off offset:256
	v_cvt_pk_bf16_f32 v60, v60, v61
	v_cvt_pk_bf16_f32 v61, v62, v63
	v_cvt_pk_bf16_f32 v62, v56, v57
	v_cvt_pk_bf16_f32 v63, v58, v59
	global_store_dwordx4 v[64:65], v[60:63], off
	v_cvt_pk_bf16_f32 v40, v52, v53
	v_cvt_pk_bf16_f32 v41, v54, v55
	v_cvt_pk_bf16_f32 v42, v44, v45
	v_cvt_pk_bf16_f32 v43, v46, v47
	global_store_dwordx4 v[48:49], v[40:43], off
	v_cvt_pk_bf16_f32 v24, v36, v37
	v_cvt_pk_bf16_f32 v25, v38, v39
	v_cvt_pk_bf16_f32 v26, v28, v29
	v_cvt_pk_bf16_f32 v27, v30, v31
	global_store_dwordx4 v[32:33], v[24:27], off
	v_cvt_pk_bf16_f32 v8, v20, v21
	v_cvt_pk_bf16_f32 v9, v22, v23
	v_cvt_pk_bf16_f32 v10, v12, v13
	v_cvt_pk_bf16_f32 v11, v14, v15
	global_store_dwordx4 v[16:17], v[8:11], off
	v_cvt_pk_bf16_f32 v4, v4, v5
	v_cvt_pk_bf16_f32 v5, v6, v7
	v_cvt_pk_bf16_f32 v6, v0, v1
	v_cvt_pk_bf16_f32 v7, v2, v3
	global_store_dwordx4 v[16:17], v[4:7], off offset:256
	s_cbranch_vccz .LBB0_118
	s_waitcnt vmcnt(0)
	s_cmpk_gt_u32 s24, 0xff
	s_cbranch_scc1 .LBB0_129
	s_barrier

; #define PG8_STAGE(bufoff, gbase, voff) do { _Pragma("unroll") for (int _i = 0; _i < 2; ++_i) \
;         __builtin_amdgcn_global_load_lds((const unsigned*)((const char*)(gbase) + (voff)[_i]), (LAS unsigned*)(lds + (bufoff) + ldsw + _i * 8192), 16, 0, 0); } while (0)
; #define PG8_LDA(dst, b, h) do { _Pragma("unroll") for (int m = 0; m < 4; ++m) _Pragma("unroll") for (int k = 0; k < 2; ++k) dst[m][k] = *(const LAS bf16x8*)(lds + PG8_SA(b, h) + aoff + m * 2048 + k * 1024); } while (0)
; #define PG8_LDB(dst, b, h) do { _Pragma("unroll") for (int n = 0; n < 2; ++n) _Pragma("unroll") for (int k = 0; k < 2; ++k) dst[n][k] = *(const LAS bf16x8*)(lds + PG8_SB(b, h) + boff + n * 2048 + k * 1024); } while (0)
; #define PG8_MMA(ai, bj, At, Bt) do { __builtin_amdgcn_s_setprio(1); _Pragma("unroll") for (int m = 0; m < 4; ++m) _Pragma("unroll") for (int n = 0; n < 2; ++n) _Pragma("unroll") for (int k = 0; k < 2; ++k) \
;         acc[ai][bj][m][n] = __builtin_amdgcn_mfma_f32_16x16x32_bf16(Bt[n][k], At[m][k], acc[ai][bj][m][n], 0, 0, 0); __builtin_amdgcn_s_setprio(0); } while (0)
; #define PG8_WAIT_V(n) asm volatile("s_waitcnt vmcnt(" #n ")" ::: "memory")
; #define PG8_WAIT_L(n) asm volatile("s_waitcnt lgkmcnt(" #n ")" ::: "memory")
; #define PG8_BAR __builtin_amdgcn_s_barrier()
; #define PG8_SCHED __builtin_amdgcn_sched_barrier(0)
; template <class Epi, class Sched>
; __device__ __forceinline__ void gemm_phase(LAS unsigned char* lds, const Gemm g, const Sched& S, const Epi& E) {
;     ...
;             PG8_LDB(B0, 0, 0); PG8_SCHED; PG8_LDA(At, 0, 0); PG8_STAGE(PG8_SA(1, 1), a1 + hstep, voffA);
;             PG8_WAIT_L(8); PG8_BAR; PG8_WAIT_L(0); PG8_MMA(0, 0, At, B0); PG8_BAR; PG8_SCHED;
;             PG8_LDB(B1, 0, 1); PG8_STAGE(PG8_SB(0, 0), b2, voffB);
;             PG8_BAR; PG8_WAIT_L(0); PG8_MMA(0, 1, At, B1); PG8_BAR;
;             PG8_LDA(At, 0, 1); PG8_STAGE(PG8_SA(0, 0), a2, voffA);
;             PG8_BAR; PG8_WAIT_L(0); PG8_MMA(1, 0, At, B0); PG8_BAR; PG8_SCHED;
;             PG8_STAGE(PG8_SB(0, 1), b2 + hstep, voffB);
;             PG8_WAIT_V(6); PG8_BAR; PG8_MMA(1, 1, At, B1); PG8_BAR;
.LBB0_170:
	s_add_i32 s53, s22, 2
	s_add_u32 s20, s16, 0x100
	s_addc_u32 s21, s17, 0
	s_add_i32 s54, 0, 0x10000
	ds_read_b128 v[128:131], v141
	ds_read_b128 v[132:135], v141 offset:1024
	ds_read_b128 v[136:139], v141 offset:2048
	ds_read_b128 v[160:163], v141 offset:3072
	s_cmp_eq_u32 s15, s22
	s_cselect_b32 s22, s4, s51
	s_cselect_b32 s25, s7, s21
	s_cselect_b32 s24, s6, s20
	s_cselect_b32 s23, s5, s52
	s_add_i32 m0, s35, 0xc000
	ds_read_b128 v[164:167], v173
	ds_read_b128 v[174:177], v173 offset:1024
	ds_read_b128 v[200:203], v173 offset:2048
	ds_read_b128 v[204:207], v173 offset:3072
	ds_read_b128 v[208:211], v173 offset:4096
	ds_read_b128 v[212:215], v173 offset:5120
	ds_read_b128 v[216:219], v173 offset:6144
	ds_read_b128 v[220:223], v173 offset:7168
	global_load_lds_dwordx4 v142, s[16:17]
	s_add_i32 m0, s35, 0xe000
	s_nop 0
	global_load_lds_dwordx4 v144, s[16:17]
	s_waitcnt lgkmcnt(8)
	s_barrier
	s_waitcnt lgkmcnt(0)
	v_mfma_f32_16x16x32_bf16 v[124:127], v[128:131], v[164:167], v[124:127]
	v_mfma_f32_16x16x32_bf16 v[120:123], v[136:139], v[164:167], v[120:123]
	v_mfma_f32_16x16x32_bf16 v[116:119], v[128:131], v[200:203], v[116:119]
	v_mfma_f32_16x16x32_bf16 v[112:115], v[136:139], v[200:203], v[112:115]
	v_mfma_f32_16x16x32_bf16 v[100:103], v[128:131], v[208:211], v[100:103]
	v_mfma_f32_16x16x32_bf16 v[96:99], v[136:139], v[208:211], v[96:99]
	v_mfma_f32_16x16x32_bf16 v[84:87], v[128:131], v[216:219], v[84:87]
	v_mfma_f32_16x16x32_bf16 v[80:83], v[136:139], v[216:219], v[80:83]
	v_mfma_f32_16x16x32_bf16 v[124:127], v[132:135], v[174:177], v[124:127]
	v_mfma_f32_16x16x32_bf16 v[120:123], v[160:163], v[174:177], v[120:123]
	v_mfma_f32_16x16x32_bf16 v[116:119], v[132:135], v[204:207], v[116:119]
	v_mfma_f32_16x16x32_bf16 v[112:115], v[160:163], v[204:207], v[112:115]
	v_mfma_f32_16x16x32_bf16 v[100:103], v[132:135], v[212:215], v[100:103]
	v_mfma_f32_16x16x32_bf16 v[96:99], v[160:163], v[212:215], v[96:99]
	v_mfma_f32_16x16x32_bf16 v[84:87], v[132:135], v[220:223], v[84:87]
	v_mfma_f32_16x16x32_bf16 v[80:83], v[160:163], v[220:223], v[80:83]
	s_barrier
	s_add_i32 s55, 0, 0x14000
	s_add_i32 s16, s54, s29
	ds_read_b128 v[224:227], v141 offset:16384
	ds_read_b128 v[228:231], v141 offset:17408
	ds_read_b128 v[232:235], v141 offset:18432
	ds_read_b128 v[236:239], v141 offset:19456
	s_add_u32 s84, s22, 0x80
	s_addc_u32 s85, s23, 0
	s_mov_b32 m0, s16
	s_nop 0
	global_load_lds_dwordx4 v148, s[22:23]
	s_add_i32 m0, s16, 0x2000
	s_nop 0
	global_load_lds_dwordx4 v140, s[22:23]
	s_barrier
	s_waitcnt lgkmcnt(0)
	v_mfma_f32_16x16x32_bf16 v[108:111], v[224:227], v[164:167], v[108:111]
	v_mfma_f32_16x16x32_bf16 v[104:107], v[232:235], v[164:167], v[104:107]
	v_mfma_f32_16x16x32_bf16 v[92:95], v[224:227], v[200:203], v[92:95]
	v_mfma_f32_16x16x32_bf16 v[88:91], v[232:235], v[200:203], v[88:91]
	v_mfma_f32_16x16x32_bf16 v[76:79], v[224:227], v[208:211], v[76:79]
	v_mfma_f32_16x16x32_bf16 v[72:75], v[232:235], v[208:211], v[72:75]
	v_mfma_f32_16x16x32_bf16 v[68:71], v[224:227], v[216:219], v[68:71]
	v_mfma_f32_16x16x32_bf16 v[64:67], v[232:235], v[216:219], v[64:67]
	v_mfma_f32_16x16x32_bf16 v[108:111], v[228:231], v[174:177], v[108:111]
	v_mfma_f32_16x16x32_bf16 v[104:107], v[236:239], v[174:177], v[104:107]
	v_mfma_f32_16x16x32_bf16 v[92:95], v[228:231], v[204:207], v[92:95]
	v_mfma_f32_16x16x32_bf16 v[88:91], v[236:239], v[204:207], v[88:91]
	v_mfma_f32_16x16x32_bf16 v[76:79], v[228:231], v[212:215], v[76:79]
	v_mfma_f32_16x16x32_bf16 v[72:75], v[236:239], v[212:215], v[72:75]
	v_mfma_f32_16x16x32_bf16 v[68:71], v[228:231], v[220:223], v[68:71]
	v_mfma_f32_16x16x32_bf16 v[64:67], v[236:239], v[220:223], v[64:67]
	s_mov_b32 m0, s35
	s_add_u32 s86, s24, 0x80
	s_addc_u32 s87, s25, 0
	s_barrier
	ds_read_b128 v[164:167], v173 offset:16384
	ds_read_b128 v[174:177], v173 offset:17408
	ds_read_b128 v[200:203], v173 offset:18432
	ds_read_b128 v[204:207], v173 offset:19456
	ds_read_b128 v[208:211], v173 offset:20480
	ds_read_b128 v[212:215], v173 offset:21504
	ds_read_b128 v[216:219], v173 offset:22528
	ds_read_b128 v[220:223], v173 offset:23552
	global_load_lds_dwordx4 v148, s[24:25]
	s_mov_b32 m0, s36
	s_nop 0
	global_load_lds_dwordx4 v140, s[24:25]
	s_barrier
	s_waitcnt lgkmcnt(0)
	v_mfma_f32_16x16x32_bf16 v[60:63], v[128:131], v[164:167], v[60:63]
	v_mfma_f32_16x16x32_bf16 v[56:59], v[136:139], v[164:167], v[56:59]
	v_mfma_f32_16x16x32_bf16 v[52:55], v[128:131], v[200:203], v[52:55]
	v_mfma_f32_16x16x32_bf16 v[48:51], v[136:139], v[200:203], v[48:51]
	v_mfma_f32_16x16x32_bf16 v[36:39], v[128:131], v[208:211], v[36:39]
	v_mfma_f32_16x16x32_bf16 v[32:35], v[136:139], v[208:211], v[32:35]
	v_mfma_f32_16x16x32_bf16 v[20:23], v[128:131], v[216:219], v[20:23]
	v_mfma_f32_16x16x32_bf16 v[16:19], v[136:139], v[216:219], v[16:19]
	v_mfma_f32_16x16x32_bf16 v[60:63], v[132:135], v[174:177], v[60:63]
	v_mfma_f32_16x16x32_bf16 v[56:59], v[160:163], v[174:177], v[56:59]
	v_mfma_f32_16x16x32_bf16 v[52:55], v[132:135], v[204:207], v[52:55]
	v_mfma_f32_16x16x32_bf16 v[48:51], v[160:163], v[204:207], v[48:51]
	v_mfma_f32_16x16x32_bf16 v[36:39], v[132:135], v[212:215], v[36:39]
	v_mfma_f32_16x16x32_bf16 v[32:35], v[160:163], v[212:215], v[32:35]
	v_mfma_f32_16x16x32_bf16 v[20:23], v[132:135], v[220:223], v[20:23]
	v_mfma_f32_16x16x32_bf16 v[16:19], v[160:163], v[220:223], v[16:19]
	s_barrier
	s_add_u32 s16, s22, 0x160000
	s_addc_u32 s17, s23, 0
	s_add_i32 s54, s55, s29
	s_mov_b32 m0, s54
	s_nop 0
	global_load_lds_dwordx4 v148, s[16:17]
	s_add_i32 m0, s54, 0x2000
	s_nop 0
	global_load_lds_dwordx4 v140, s[16:17]
	s_waitcnt vmcnt(6)
	s_barrier
; #define PG8_STAGE(bufoff, gbase, voff) do { _Pragma("unroll") for (int _i = 0; _i < 2; ++_i) \
;         __builtin_amdgcn_global_load_lds((const unsigned*)((const char*)(gbase) + (voff)[_i]), (LAS unsigned*)(lds + (bufoff) + ldsw + _i * 8192), 16, 0, 0); } while (0)
; #define PG8_LDA(dst, b, h) do { _Pragma("unroll") for (int m = 0; m < 4; ++m) _Pragma("unroll") for (int k = 0; k < 2; ++k) dst[m][k] = *(const LAS bf16x8*)(lds + PG8_SA(b, h) + aoff + m * 2048 + k * 1024); } while (0)
; #define PG8_LDB(dst, b, h) do { _Pragma("unroll") for (int n = 0; n < 2; ++n) _Pragma("unroll") for (int k = 0; k < 2; ++k) dst[n][k] = *(const LAS bf16x8*)(lds + PG8_SB(b, h) + boff + n * 2048 + k * 1024); } while (0)
; #define PG8_MMA(ai, bj, At, Bt) do { __builtin_amdgcn_s_setprio(1); _Pragma("unroll") for (int m = 0; m < 4; ++m) _Pragma("unroll") for (int n = 0; n < 2; ++n) _Pragma("unroll") for (int k = 0; k < 2; ++k) \
;         acc[ai][bj][m][n] = __builtin_amdgcn_mfma_f32_16x16x32_bf16(Bt[n][k], At[m][k], acc[ai][bj][m][n], 0, 0, 0); __builtin_amdgcn_s_setprio(0); } while (0)
; #define PG8_WAIT_V(n) asm volatile("s_waitcnt vmcnt(" #n ")" ::: "memory")
; #define PG8_WAIT_L(n) asm volatile("s_waitcnt lgkmcnt(" #n ")" ::: "memory")
; #define PG8_BAR __builtin_amdgcn_s_barrier()
; #define PG8_SCHED __builtin_amdgcn_sched_barrier(0)
; template <class Epi, class Sched>
; __device__ __forceinline__ void gemm_phase(LAS unsigned char* lds, const Gemm g, const Sched& S, const Epi& E) {
;     ...
;             PG8_WAIT_V(6); PG8_BAR; PG8_MMA(1, 1, At, B1); PG8_BAR;
;             PG8_LDB(B0, 1, 0); PG8_SCHED; PG8_LDA(At, 1, 0); PG8_STAGE(PG8_SA(0, 1), a2 + hstep, voffA);
;             PG8_WAIT_L(8); PG8_BAR; PG8_WAIT_L(0); PG8_MMA(0, 0, At, B0); PG8_BAR; PG8_SCHED;
;             PG8_LDB(B1, 1, 1); PG8_STAGE(PG8_SB(1, 0), b3, voffB);
;             PG8_BAR; PG8_WAIT_L(0); PG8_MMA(0, 1, At, B1); PG8_BAR;
;             PG8_LDA(At, 1, 1); PG8_STAGE(PG8_SA(1, 0), a3, voffA);
;             PG8_BAR; PG8_WAIT_L(0); PG8_MMA(1, 0, At, B0); PG8_BAR; PG8_SCHED;
	v_mfma_f32_16x16x32_bf16 v[44:47], v[224:227], v[164:167], v[44:47]
	v_mfma_f32_16x16x32_bf16 v[40:43], v[232:235], v[164:167], v[40:43]
	v_mfma_f32_16x16x32_bf16 v[28:31], v[224:227], v[200:203], v[28:31]
	v_mfma_f32_16x16x32_bf16 v[24:27], v[232:235], v[200:203], v[24:27]
	v_mfma_f32_16x16x32_bf16 v[12:15], v[224:227], v[208:211], v[12:15]
	v_mfma_f32_16x16x32_bf16 v[8:11], v[232:235], v[208:211], v[8:11]
	v_mfma_f32_16x16x32_bf16 v[4:7], v[224:227], v[216:219], v[4:7]
	v_mfma_f32_16x16x32_bf16 v[0:3], v[232:235], v[216:219], v[0:3]
	v_mfma_f32_16x16x32_bf16 v[44:47], v[228:231], v[174:177], v[44:47]
	v_mfma_f32_16x16x32_bf16 v[40:43], v[236:239], v[174:177], v[40:43]
	v_mfma_f32_16x16x32_bf16 v[28:31], v[228:231], v[204:207], v[28:31]
	v_mfma_f32_16x16x32_bf16 v[24:27], v[236:239], v[204:207], v[24:27]
	v_mfma_f32_16x16x32_bf16 v[12:15], v[228:231], v[212:215], v[12:15]
	v_mfma_f32_16x16x32_bf16 v[8:11], v[236:239], v[212:215], v[8:11]
	v_mfma_f32_16x16x32_bf16 v[4:7], v[228:231], v[220:223], v[4:7]
	v_mfma_f32_16x16x32_bf16 v[0:3], v[236:239], v[220:223], v[0:3]
	s_add_i32 s54, 0, 0x18000
	s_barrier
	ds_read_b128 v[128:131], v141 offset:32768
	ds_read_b128 v[132:135], v141 offset:33792
	ds_read_b128 v[136:139], v141 offset:34816
	ds_read_b128 v[160:163], v141 offset:35840
	s_add_u32 s16, s24, 0x160000
	s_addc_u32 s17, s25, 0
	s_mov_b32 m0, s37
	ds_read_b128 v[164:167], v173 offset:32768
	ds_read_b128 v[174:177], v173 offset:33792
	ds_read_b128 v[200:203], v173 offset:34816
	ds_read_b128 v[204:207], v173 offset:35840
	ds_read_b128 v[208:211], v173 offset:36864
	ds_read_b128 v[212:215], v173 offset:37888
	ds_read_b128 v[216:219], v173 offset:38912
	ds_read_b128 v[220:223], v173 offset:39936
	global_load_lds_dwordx4 v148, s[16:17]
	s_mov_b32 m0, s38
	s_nop 0
	global_load_lds_dwordx4 v140, s[16:17]
	s_waitcnt lgkmcnt(8)
	s_barrier
	s_waitcnt lgkmcnt(0)
	v_mfma_f32_16x16x32_bf16 v[124:127], v[128:131], v[164:167], v[124:127]
	v_mfma_f32_16x16x32_bf16 v[120:123], v[136:139], v[164:167], v[120:123]
	v_mfma_f32_16x16x32_bf16 v[116:119], v[128:131], v[200:203], v[116:119]
	v_mfma_f32_16x16x32_bf16 v[112:115], v[136:139], v[200:203], v[112:115]
	v_mfma_f32_16x16x32_bf16 v[100:103], v[128:131], v[208:211], v[100:103]
	v_mfma_f32_16x16x32_bf16 v[96:99], v[136:139], v[208:211], v[96:99]
	v_mfma_f32_16x16x32_bf16 v[84:87], v[128:131], v[216:219], v[84:87]
	v_mfma_f32_16x16x32_bf16 v[80:83], v[136:139], v[216:219], v[80:83]
	v_mfma_f32_16x16x32_bf16 v[124:127], v[132:135], v[174:177], v[124:127]
	v_mfma_f32_16x16x32_bf16 v[120:123], v[160:163], v[174:177], v[120:123]
	v_mfma_f32_16x16x32_bf16 v[116:119], v[132:135], v[204:207], v[116:119]
	v_mfma_f32_16x16x32_bf16 v[112:115], v[160:163], v[204:207], v[112:115]
	v_mfma_f32_16x16x32_bf16 v[100:103], v[132:135], v[212:215], v[100:103]
	v_mfma_f32_16x16x32_bf16 v[96:99], v[160:163], v[212:215], v[96:99]
	v_mfma_f32_16x16x32_bf16 v[84:87], v[132:135], v[220:223], v[84:87]
	v_mfma_f32_16x16x32_bf16 v[80:83], v[160:163], v[220:223], v[80:83]
	s_barrier
	s_add_i32 s24, 0, 0x1c000
	s_add_i32 s16, s54, s29
	s_mov_b32 m0, s16
	ds_read_b128 v[224:227], v141 offset:49152
	ds_read_b128 v[228:231], v141 offset:50176
	ds_read_b128 v[232:235], v141 offset:51200
	ds_read_b128 v[236:239], v141 offset:52224
	global_load_lds_dwordx4 v148, s[84:85]
	s_add_i32 m0, s16, 0x2000
	s_nop 0
	global_load_lds_dwordx4 v140, s[84:85]
	s_barrier
	s_waitcnt lgkmcnt(0)
	v_mfma_f32_16x16x32_bf16 v[108:111], v[224:227], v[164:167], v[108:111]
	v_mfma_f32_16x16x32_bf16 v[104:107], v[232:235], v[164:167], v[104:107]
	v_mfma_f32_16x16x32_bf16 v[92:95], v[224:227], v[200:203], v[92:95]
	v_mfma_f32_16x16x32_bf16 v[88:91], v[232:235], v[200:203], v[88:91]
	v_mfma_f32_16x16x32_bf16 v[76:79], v[224:227], v[208:211], v[76:79]
	v_mfma_f32_16x16x32_bf16 v[72:75], v[232:235], v[208:211], v[72:75]
	v_mfma_f32_16x16x32_bf16 v[68:71], v[224:227], v[216:219], v[68:71]
	v_mfma_f32_16x16x32_bf16 v[64:67], v[232:235], v[216:219], v[64:67]
	v_mfma_f32_16x16x32_bf16 v[108:111], v[228:231], v[174:177], v[108:111]
	v_mfma_f32_16x16x32_bf16 v[104:107], v[236:239], v[174:177], v[104:107]
	v_mfma_f32_16x16x32_bf16 v[92:95], v[228:231], v[204:207], v[92:95]
	v_mfma_f32_16x16x32_bf16 v[88:91], v[236:239], v[204:207], v[88:91]
	v_mfma_f32_16x16x32_bf16 v[76:79], v[228:231], v[212:215], v[76:79]
	v_mfma_f32_16x16x32_bf16 v[72:75], v[236:239], v[212:215], v[72:75]
	v_mfma_f32_16x16x32_bf16 v[68:71], v[228:231], v[220:223], v[68:71]
	v_mfma_f32_16x16x32_bf16 v[64:67], v[236:239], v[220:223], v[64:67]
	s_mov_b32 m0, s41
	s_barrier
	ds_read_b128 v[164:167], v173 offset:49152
	ds_read_b128 v[174:177], v173 offset:50176
	ds_read_b128 v[200:203], v173 offset:51200
	ds_read_b128 v[204:207], v173 offset:52224
	ds_read_b128 v[208:211], v173 offset:53248
	ds_read_b128 v[212:215], v173 offset:54272
	ds_read_b128 v[216:219], v173 offset:55296
	ds_read_b128 v[220:223], v173 offset:56320
	global_load_lds_dwordx4 v148, s[86:87]
	s_mov_b32 m0, s42
	s_nop 0
	global_load_lds_dwordx4 v140, s[86:87]
	s_barrier
	s_waitcnt lgkmcnt(0)
	v_mfma_f32_16x16x32_bf16 v[60:63], v[128:131], v[164:167], v[60:63]
	v_mfma_f32_16x16x32_bf16 v[56:59], v[136:139], v[164:167], v[56:59]
	v_mfma_f32_16x16x32_bf16 v[52:55], v[128:131], v[200:203], v[52:55]
	v_mfma_f32_16x16x32_bf16 v[48:51], v[136:139], v[200:203], v[48:51]
	v_mfma_f32_16x16x32_bf16 v[36:39], v[128:131], v[208:211], v[36:39]
	v_mfma_f32_16x16x32_bf16 v[32:35], v[136:139], v[208:211], v[32:35]
	v_mfma_f32_16x16x32_bf16 v[20:23], v[128:131], v[216:219], v[20:23]
	v_mfma_f32_16x16x32_bf16 v[16:19], v[136:139], v[216:219], v[16:19]
	v_mfma_f32_16x16x32_bf16 v[60:63], v[132:135], v[174:177], v[60:63]
	v_mfma_f32_16x16x32_bf16 v[56:59], v[160:163], v[174:177], v[56:59]
	v_mfma_f32_16x16x32_bf16 v[52:55], v[132:135], v[204:207], v[52:55]
	v_mfma_f32_16x16x32_bf16 v[48:51], v[160:163], v[204:207], v[48:51]
	v_mfma_f32_16x16x32_bf16 v[36:39], v[132:135], v[212:215], v[36:39]
	v_mfma_f32_16x16x32_bf16 v[32:35], v[160:163], v[212:215], v[32:35]
	v_mfma_f32_16x16x32_bf16 v[20:23], v[132:135], v[220:223], v[20:23]
	v_mfma_f32_16x16x32_bf16 v[16:19], v[160:163], v[220:223], v[16:19]
	s_barrier
; #define PG8_STAGE(bufoff, gbase, voff) do { _Pragma("unroll") for (int _i = 0; _i < 2; ++_i) \
;         __builtin_amdgcn_global_load_lds((const unsigned*)((const char*)(gbase) + (voff)[_i]), (LAS unsigned*)(lds + (bufoff) + ldsw + _i * 8192), 16, 0, 0); } while (0)
; #define PG8_MMA(ai, bj, At, Bt) do { __builtin_amdgcn_s_setprio(1); _Pragma("unroll") for (int m = 0; m < 4; ++m) _Pragma("unroll") for (int n = 0; n < 2; ++n) _Pragma("unroll") for (int k = 0; k < 2; ++k) \
;         acc[ai][bj][m][n] = __builtin_amdgcn_mfma_f32_16x16x32_bf16(Bt[n][k], At[m][k], acc[ai][bj][m][n], 0, 0, 0); __builtin_amdgcn_s_setprio(0); } while (0)
; #define PG8_WAIT_V(n) asm volatile("s_waitcnt vmcnt(" #n ")" ::: "memory")
; #define PG8_WAIT_L(n) asm volatile("s_waitcnt lgkmcnt(" #n ")" ::: "memory")
; #define PG8_BAR __builtin_amdgcn_s_barrier()
; #define PG8_SCHED __builtin_amdgcn_sched_barrier(0)
;     __device__ __forceinline__ void operator()(const f32x4 (&acc)[2][2][4][2], const Unit& u, int wr, int wc, int fr, int fq) const {
;     ...
;         const float* base = (u.pm < 32) ? base_lo : base_hi;
; #pragma unroll
;         for (int ai = 0; ai < 2; ++ai) {
;             f32x4 bs[4][2][2];
; #pragma unroll
;             for (int m = 0; m < 4; ++m) { const size_t off = (size_t)(row0 + ai * HALF + m * 16) * DM + col0;
; #pragma unroll
;                 for (int bj = 0; bj < 2; ++bj)
; #pragma unroll
;                     for (int n = 0; n < 2; ++n) bs[m][bj][n] = *(const f32x4*)(base + off + bj * HALF + n * 16); }
; #pragma unroll
;             for (int m = 0; m < 4; ++m) { const size_t off = (size_t)(row0 + ai * HALF + m * 16) * DM + col0;
; #pragma unroll
;                 for (int bj = 0; bj < 2; ++bj)
; #pragma unroll
;                     for (int n = 0; n < 2; ++n) *(f32x4*)(out + off + bj * HALF + n * 16) = bs[m][bj][n] + scale * acc[ai][bj][m][n]; }
; template <class Epi, class Sched>
; __device__ __forceinline__ void gemm_phase(LAS unsigned char* lds, const Gemm g, const Sched& S, const Epi& E) {
;     ...
;             PG8_BAR; PG8_WAIT_L(0); PG8_MMA(1, 0, At, B0); PG8_BAR; PG8_SCHED;
;             PG8_STAGE(PG8_SB(1, 1), b3 + hstep, voffB);
;             PG8_WAIT_V(6); PG8_BAR; PG8_MMA(1, 1, At, B1); PG8_BAR;
	s_add_u32 s16, s22, 0x160080
	s_addc_u32 s17, s23, 0
	s_add_i32 s22, s24, s29
	s_mov_b32 m0, s22
	s_nop 0
	global_load_lds_dwordx4 v148, s[16:17]
	s_add_i32 m0, s22, 0x2000
	s_nop 0
	global_load_lds_dwordx4 v140, s[16:17]
	s_waitcnt vmcnt(6)
	s_barrier
	v_mfma_f32_16x16x32_bf16 v[44:47], v[224:227], v[164:167], v[44:47]
	v_mfma_f32_16x16x32_bf16 v[40:43], v[232:235], v[164:167], v[40:43]
	v_mfma_f32_16x16x32_bf16 v[28:31], v[224:227], v[200:203], v[28:31]
	v_mfma_f32_16x16x32_bf16 v[24:27], v[232:235], v[200:203], v[24:27]
	v_mfma_f32_16x16x32_bf16 v[12:15], v[224:227], v[208:211], v[12:15]
	v_mfma_f32_16x16x32_bf16 v[8:11], v[232:235], v[208:211], v[8:11]
	v_mfma_f32_16x16x32_bf16 v[4:7], v[224:227], v[216:219], v[4:7]
	v_mfma_f32_16x16x32_bf16 v[0:3], v[232:235], v[216:219], v[0:3]
	v_mfma_f32_16x16x32_bf16 v[44:47], v[228:231], v[174:177], v[44:47]
	v_mfma_f32_16x16x32_bf16 v[40:43], v[236:239], v[174:177], v[40:43]
	v_mfma_f32_16x16x32_bf16 v[28:31], v[228:231], v[204:207], v[28:31]
	v_mfma_f32_16x16x32_bf16 v[24:27], v[236:239], v[204:207], v[24:27]
	v_mfma_f32_16x16x32_bf16 v[12:15], v[228:231], v[212:215], v[12:15]
	v_mfma_f32_16x16x32_bf16 v[8:11], v[236:239], v[212:215], v[8:11]
	v_mfma_f32_16x16x32_bf16 v[4:7], v[228:231], v[220:223], v[4:7]
	v_mfma_f32_16x16x32_bf16 v[0:3], v[236:239], v[220:223], v[0:3]
	s_add_u32 s51, s51, 0x100
	s_addc_u32 s52, s52, 0
	s_cmp_ge_i32 s53, s50
	s_mov_b64 s[16:17], s[20:21]
	s_mov_b32 s22, s53
	s_barrier
	s_cbranch_scc0 .LBB0_170
	v_lshl_add_u32 v146, s48, 8, v170
	v_lshl_or_b32 v160, s49, 8, v172
	s_mov_b64 s[16:17], -1
	s_cmp_lt_i32 s82, 0
	v_ashrrev_i32_e32 v161, 31, v160
	v_ashrrev_i32_e32 v147, 31, v146
	s_cbranch_scc0 .LBB0_173
	s_cmp_lt_i32 s48, 32
	s_cselect_b32 s17, s13, s61
	s_cselect_b32 s16, s12, s60
	v_lshlrev_b64 v[162:163], 2, v[160:161]
	v_lshl_add_u64 v[164:165], s[16:17], 0, v[162:163]
	v_lshlrev_b64 v[166:167], 13, v[146:147]
	v_lshl_add_u64 v[128:129], v[164:165], 0, v[166:167]
	global_load_dwordx4 v[174:177], v[128:129], off
	global_load_dwordx4 v[200:203], v[128:129], off offset:64
	global_load_dwordx4 v[204:207], v[128:129], off offset:512
	global_load_dwordx4 v[208:211], v[128:129], off offset:576
	v_or_b32_e32 v128, 16, v146
	v_ashrrev_i32_e32 v129, 31, v128
	v_lshlrev_b64 v[248:249], 13, v[128:129]
	v_lshl_add_u64 v[128:129], v[164:165], 0, v[248:249]
	global_load_dwordx4 v[212:215], v[128:129], off
	global_load_dwordx4 v[216:219], v[128:129], off offset:64
	global_load_dwordx4 v[220:223], v[128:129], off offset:512
	global_load_dwordx4 v[224:227], v[128:129], off offset:576
	v_or_b32_e32 v128, 32, v146
	v_ashrrev_i32_e32 v129, 31, v128
	v_lshlrev_b64 v[188:189], 13, v[128:129]
	v_lshl_add_u64 v[128:129], v[164:165], 0, v[188:189]
	global_load_dwordx4 v[228:231], v[128:129], off
	global_load_dwordx4 v[232:235], v[128:129], off offset:64
	global_load_dwordx4 v[236:239], v[128:129], off offset:512
	global_load_dwordx4 v[240:243], v[128:129], off offset:576
	v_or_b32_e32 v128, 48, v146
	v_ashrrev_i32_e32 v129, 31, v128
	v_lshlrev_b64 v[168:169], 13, v[128:129]
	v_lshl_add_u64 v[128:129], v[164:165], 0, v[168:169]
	global_load_dwordx4 v[244:247], v[128:129], off
	global_load_dwordx4 v[136:139], v[128:129], off offset:64
	global_load_dwordx4 v[132:135], v[128:129], off offset:512
	s_nop 0
	global_load_dwordx4 v[128:131], v[128:129], off offset:576
	v_lshl_add_u64 v[190:191], s[60:61], 0, v[166:167]
	v_lshl_add_u64 v[190:191], v[190:191], 0, v[162:163]
	v_lshl_add_u64 v[188:189], s[60:61], 0, v[188:189]
	v_lshl_add_u64 v[188:189], v[188:189], 0, v[162:163]
	v_lshl_add_u64 v[168:169], s[60:61], 0, v[168:169]
	v_lshl_add_u64 v[168:169], v[168:169], 0, v[162:163]
	s_mov_b64 s[16:17], 0x100000
	s_waitcnt vmcnt(0)
	v_pk_fma_f32 v[176:177], v[126:127], 0.5, v[176:177] op_sel_hi:[1,0,1]
	v_pk_fma_f32 v[174:175], v[124:125], 0.5, v[174:175] op_sel_hi:[1,0,1]
	global_store_dwordx4 v[190:191], v[174:177], off
	v_pk_fma_f32 v[138:139], v[82:83], 0.5, v[138:139] op_sel_hi:[1,0,1]
	s_nop 0
	v_pk_fma_f32 v[176:177], v[122:123], 0.5, v[202:203] op_sel_hi:[1,0,1]
	v_pk_fma_f32 v[174:175], v[120:121], 0.5, v[200:201] op_sel_hi:[1,0,1]
	global_store_dwordx4 v[190:191], v[174:177], off offset:64
	v_pk_fma_f32 v[136:137], v[80:81], 0.5, v[136:137] op_sel_hi:[1,0,1]
	v_pk_fma_f32 v[134:135], v[70:71], 0.5, v[134:135] op_sel_hi:[1,0,1]
	v_pk_fma_f32 v[176:177], v[110:111], 0.5, v[206:207] op_sel_hi:[1,0,1]
	v_pk_fma_f32 v[174:175], v[108:109], 0.5, v[204:205] op_sel_hi:[1,0,1]
	global_store_dwordx4 v[190:191], v[174:177], off offset:512
	v_pk_fma_f32 v[132:133], v[68:69], 0.5, v[132:133] op_sel_hi:[1,0,1]
	v_pk_fma_f32 v[130:131], v[66:67], 0.5, v[130:131] op_sel_hi:[1,0,1]
	v_pk_fma_f32 v[176:177], v[106:107], 0.5, v[210:211] op_sel_hi:[1,0,1]
	v_pk_fma_f32 v[174:175], v[104:105], 0.5, v[208:209] op_sel_hi:[1,0,1]
	global_store_dwordx4 v[190:191], v[174:177], off offset:576
	v_lshl_add_u64 v[190:191], s[60:61], 0, v[248:249]
	v_lshl_add_u64 v[190:191], v[190:191], 0, v[162:163]
	v_pk_fma_f32 v[176:177], v[118:119], 0.5, v[214:215] op_sel_hi:[1,0,1]
	v_pk_fma_f32 v[174:175], v[116:117], 0.5, v[212:213] op_sel_hi:[1,0,1]
	global_store_dwordx4 v[190:191], v[174:177], off
	v_pk_fma_f32 v[128:129], v[64:65], 0.5, v[128:129] op_sel_hi:[1,0,1]
	global_store_dwordx4 v[168:169], v[136:139], off offset:64
	v_pk_fma_f32 v[176:177], v[114:115], 0.5, v[218:219] op_sel_hi:[1,0,1]
	v_pk_fma_f32 v[174:175], v[112:113], 0.5, v[216:217] op_sel_hi:[1,0,1]
	global_store_dwordx4 v[190:191], v[174:177], off offset:64
	global_store_dwordx4 v[168:169], v[132:135], off offset:512
	global_store_dwordx4 v[168:169], v[128:131], off offset:576
;     __device__ __forceinline__ void operator()(const f32x4 (&acc)[2][2][4][2], const Unit& u, int wr, int wc, int fr, int fq) const {
;     ...
;         const float* base = (u.pm < 32) ? base_lo : base_hi;
; #pragma unroll
;         for (int ai = 0; ai < 2; ++ai) {
;             f32x4 bs[4][2][2];
; #pragma unroll
;             for (int m = 0; m < 4; ++m) { const size_t off = (size_t)(row0 + ai * HALF + m * 16) * DM + col0;
; #pragma unroll
;                 for (int bj = 0; bj < 2; ++bj)
; #pragma unroll
;                     for (int n = 0; n < 2; ++n) bs[m][bj][n] = *(const f32x4*)(base + off + bj * HALF + n * 16); }
; #pragma unroll
;             for (int m = 0; m < 4; ++m) { const size_t off = (size_t)(row0 + ai * HALF + m * 16) * DM + col0;
; #pragma unroll
;                 for (int bj = 0; bj < 2; ++bj)
; #pragma unroll
;                     for (int n = 0; n < 2; ++n) *(f32x4*)(out + off + bj * HALF + n * 16) = bs[m][bj][n] + scale * acc[ai][bj][m][n]; }
;             asm volatile("" ::: "memory");
	v_pk_fma_f32 v[176:177], v[94:95], 0.5, v[222:223] op_sel_hi:[1,0,1]
	v_pk_fma_f32 v[174:175], v[92:93], 0.5, v[220:221] op_sel_hi:[1,0,1]
	global_store_dwordx4 v[190:191], v[174:177], off offset:512
	s_nop 1
	v_pk_fma_f32 v[176:177], v[90:91], 0.5, v[226:227] op_sel_hi:[1,0,1]
	v_pk_fma_f32 v[174:175], v[88:89], 0.5, v[224:225] op_sel_hi:[1,0,1]
	global_store_dwordx4 v[190:191], v[174:177], off offset:576
	s_nop 1
	v_pk_fma_f32 v[176:177], v[102:103], 0.5, v[230:231] op_sel_hi:[1,0,1]
	v_pk_fma_f32 v[174:175], v[100:101], 0.5, v[228:229] op_sel_hi:[1,0,1]
	global_store_dwordx4 v[188:189], v[174:177], off
	s_nop 1
	v_pk_fma_f32 v[176:177], v[98:99], 0.5, v[234:235] op_sel_hi:[1,0,1]
	v_pk_fma_f32 v[174:175], v[96:97], 0.5, v[232:233] op_sel_hi:[1,0,1]
	global_store_dwordx4 v[188:189], v[174:177], off offset:64
	s_nop 1
	v_pk_fma_f32 v[176:177], v[78:79], 0.5, v[238:239] op_sel_hi:[1,0,1]
	v_pk_fma_f32 v[174:175], v[76:77], 0.5, v[236:237] op_sel_hi:[1,0,1]
	global_store_dwordx4 v[188:189], v[174:177], off offset:512
	s_nop 1
	v_pk_fma_f32 v[176:177], v[74:75], 0.5, v[242:243] op_sel_hi:[1,0,1]
	v_pk_fma_f32 v[174:175], v[72:73], 0.5, v[240:241] op_sel_hi:[1,0,1]
	global_store_dwordx4 v[188:189], v[174:177], off offset:576
	s_nop 1
	v_pk_fma_f32 v[176:177], v[86:87], 0.5, v[246:247] op_sel_hi:[1,0,1]
	v_pk_fma_f32 v[174:175], v[84:85], 0.5, v[244:245] op_sel_hi:[1,0,1]
	global_store_dwordx4 v[168:169], v[174:177], off
	v_lshl_add_u64 v[168:169], v[166:167], 0, s[16:17]
	v_lshl_add_u64 v[128:129], v[164:165], 0, v[168:169]
	global_load_dwordx4 v[174:177], v[128:129], off
	global_load_dwordx4 v[200:203], v[128:129], off offset:64
	global_load_dwordx4 v[204:207], v[128:129], off offset:512
	global_load_dwordx4 v[208:211], v[128:129], off offset:576
	s_mov_b64 s[16:17], 0x120000
	v_lshl_add_u64 v[188:189], v[166:167], 0, s[16:17]
	v_lshl_add_u64 v[128:129], v[164:165], 0, v[188:189]
	global_load_dwordx4 v[212:215], v[128:129], off
	global_load_dwordx4 v[216:219], v[128:129], off offset:64
	global_load_dwordx4 v[220:223], v[128:129], off offset:512
	global_load_dwordx4 v[224:227], v[128:129], off offset:576
	s_mov_b64 s[16:17], 0x140000
	v_lshl_add_u64 v[190:191], v[166:167], 0, s[16:17]
	v_lshl_add_u64 v[128:129], v[164:165], 0, v[190:191]
	s_mov_b64 s[16:17], 0x160000
	global_load_dwordx4 v[228:231], v[128:129], off
	global_load_dwordx4 v[232:235], v[128:129], off offset:64
	global_load_dwordx4 v[236:239], v[128:129], off offset:512
	global_load_dwordx4 v[240:243], v[128:129], off offset:576
	v_lshl_add_u64 v[166:167], v[166:167], 0, s[16:17]
	v_lshl_add_u64 v[128:129], v[164:165], 0, v[166:167]
	global_load_dwordx4 v[244:247], v[128:129], off
	global_load_dwordx4 v[136:139], v[128:129], off offset:64
	global_load_dwordx4 v[132:135], v[128:129], off offset:512
	s_nop 0
	global_load_dwordx4 v[128:131], v[128:129], off offset:576
	v_lshl_add_u64 v[164:165], s[60:61], 0, v[168:169]
	v_lshl_add_u64 v[164:165], v[164:165], 0, v[162:163]
	s_mov_b64 s[16:17], 0
	s_waitcnt vmcnt(0)
	v_pk_fma_f32 v[176:177], v[62:63], 0.5, v[176:177] op_sel_hi:[1,0,1]
	v_pk_fma_f32 v[174:175], v[60:61], 0.5, v[174:175] op_sel_hi:[1,0,1]
	global_store_dwordx4 v[164:165], v[174:177], off
	v_pk_fma_f32 v[138:139], v[18:19], 0.5, v[138:139] op_sel_hi:[1,0,1]
	s_nop 0
	v_pk_fma_f32 v[176:177], v[58:59], 0.5, v[202:203] op_sel_hi:[1,0,1]
	v_pk_fma_f32 v[174:175], v[56:57], 0.5, v[200:201] op_sel_hi:[1,0,1]
	global_store_dwordx4 v[164:165], v[174:177], off offset:64
	v_pk_fma_f32 v[136:137], v[16:17], 0.5, v[136:137] op_sel_hi:[1,0,1]
	v_pk_fma_f32 v[134:135], v[6:7], 0.5, v[134:135] op_sel_hi:[1,0,1]
	v_pk_fma_f32 v[176:177], v[46:47], 0.5, v[206:207] op_sel_hi:[1,0,1]
	v_pk_fma_f32 v[174:175], v[44:45], 0.5, v[204:205] op_sel_hi:[1,0,1]
	global_store_dwordx4 v[164:165], v[174:177], off offset:512
	v_pk_fma_f32 v[132:133], v[4:5], 0.5, v[132:133] op_sel_hi:[1,0,1]
	v_pk_fma_f32 v[130:131], v[2:3], 0.5, v[130:131] op_sel_hi:[1,0,1]
	v_pk_fma_f32 v[176:177], v[42:43], 0.5, v[210:211] op_sel_hi:[1,0,1]
	v_pk_fma_f32 v[174:175], v[40:41], 0.5, v[208:209] op_sel_hi:[1,0,1]
	global_store_dwordx4 v[164:165], v[174:177], off offset:576
	v_lshl_add_u64 v[164:165], s[60:61], 0, v[188:189]
	v_lshl_add_u64 v[164:165], v[164:165], 0, v[162:163]
	v_pk_fma_f32 v[176:177], v[54:55], 0.5, v[214:215] op_sel_hi:[1,0,1]
	v_pk_fma_f32 v[174:175], v[52:53], 0.5, v[212:213] op_sel_hi:[1,0,1]
	global_store_dwordx4 v[164:165], v[174:177], off
	v_pk_fma_f32 v[128:129], v[0:1], 0.5, v[128:129] op_sel_hi:[1,0,1]
	s_nop 0
	v_pk_fma_f32 v[176:177], v[50:51], 0.5, v[218:219] op_sel_hi:[1,0,1]
	v_pk_fma_f32 v[174:175], v[48:49], 0.5, v[216:217] op_sel_hi:[1,0,1]
	global_store_dwordx4 v[164:165], v[174:177], off offset:64
	s_nop 1
	v_pk_fma_f32 v[176:177], v[30:31], 0.5, v[222:223] op_sel_hi:[1,0,1]
	v_pk_fma_f32 v[174:175], v[28:29], 0.5, v[220:221] op_sel_hi:[1,0,1]
	global_store_dwordx4 v[164:165], v[174:177], off offset:512
	s_nop 1
	v_pk_fma_f32 v[176:177], v[26:27], 0.5, v[226:227] op_sel_hi:[1,0,1]
	v_pk_fma_f32 v[174:175], v[24:25], 0.5, v[224:225] op_sel_hi:[1,0,1]
	global_store_dwordx4 v[164:165], v[174:177], off offset:576
	v_lshl_add_u64 v[164:165], s[60:61], 0, v[190:191]
	v_lshl_add_u64 v[164:165], v[164:165], 0, v[162:163]
	v_pk_fma_f32 v[176:177], v[38:39], 0.5, v[230:231] op_sel_hi:[1,0,1]
	v_pk_fma_f32 v[174:175], v[36:37], 0.5, v[228:229] op_sel_hi:[1,0,1]
	global_store_dwordx4 v[164:165], v[174:177], off
	s_nop 1
	v_pk_fma_f32 v[176:177], v[34:35], 0.5, v[234:235] op_sel_hi:[1,0,1]
	v_pk_fma_f32 v[174:175], v[32:33], 0.5, v[232:233] op_sel_hi:[1,0,1]
	global_store_dwordx4 v[164:165], v[174:177], off offset:64
	s_nop 1
	v_pk_fma_f32 v[176:177], v[14:15], 0.5, v[238:239] op_sel_hi:[1,0,1]
	v_pk_fma_f32 v[174:175], v[12:13], 0.5, v[236:237] op_sel_hi:[1,0,1]
	global_store_dwordx4 v[164:165], v[174:177], off offset:512
	s_nop 1
	v_pk_fma_f32 v[176:177], v[10:11], 0.5, v[242:243] op_sel_hi:[1,0,1]
	v_pk_fma_f32 v[174:175], v[8:9], 0.5, v[240:241] op_sel_hi:[1,0,1]
	global_store_dwordx4 v[164:165], v[174:177], off offset:576
	v_lshl_add_u64 v[164:165], s[60:61], 0, v[166:167]
	v_lshl_add_u64 v[162:163], v[164:165], 0, v[162:163]
	v_pk_fma_f32 v[176:177], v[22:23], 0.5, v[246:247] op_sel_hi:[1,0,1]
	v_pk_fma_f32 v[174:175], v[20:21], 0.5, v[244:245] op_sel_hi:[1,0,1]
	global_store_dwordx4 v[162:163], v[174:177], off
	global_store_dwordx4 v[162:163], v[136:139], off offset:64
	global_store_dwordx4 v[162:163], v[132:135], off offset:512
	global_store_dwordx4 v[162:163], v[128:131], off offset:576

; #define PG8_STAGE(bufoff, gbase, voff) do { _Pragma("unroll") for (int _i = 0; _i < 2; ++_i) \
;         __builtin_amdgcn_global_load_lds((const unsigned*)((const char*)(gbase) + (voff)[_i]), (LAS unsigned*)(lds + (bufoff) + ldsw + _i * 8192), 16, 0, 0); } while (0)
; #define PG8_LDA(dst, b, h) do { _Pragma("unroll") for (int m = 0; m < 4; ++m) _Pragma("unroll") for (int k = 0; k < 2; ++k) dst[m][k] = *(const LAS bf16x8*)(lds + PG8_SA(b, h) + aoff + m * 2048 + k * 1024); } while (0)
; #define PG8_LDB(dst, b, h) do { _Pragma("unroll") for (int n = 0; n < 2; ++n) _Pragma("unroll") for (int k = 0; k < 2; ++k) dst[n][k] = *(const LAS bf16x8*)(lds + PG8_SB(b, h) + boff + n * 2048 + k * 1024); } while (0)
; #define PG8_MMA(ai, bj, At, Bt) do { __builtin_amdgcn_s_setprio(1); _Pragma("unroll") for (int m = 0; m < 4; ++m) _Pragma("unroll") for (int n = 0; n < 2; ++n) _Pragma("unroll") for (int k = 0; k < 2; ++k) \
;         acc[ai][bj][m][n] = __builtin_amdgcn_mfma_f32_16x16x32_bf16(Bt[n][k], At[m][k], acc[ai][bj][m][n], 0, 0, 0); __builtin_amdgcn_s_setprio(0); } while (0)
; #define PG8_WAIT_V(n) asm volatile("s_waitcnt vmcnt(" #n ")" ::: "memory")
; #define PG8_WAIT_L(n) asm volatile("s_waitcnt lgkmcnt(" #n ")" ::: "memory")
; #define PG8_BAR __builtin_amdgcn_s_barrier()
; #define PG8_SCHED __builtin_amdgcn_sched_barrier(0)
; template <class Epi, class Sched>
; __device__ __forceinline__ void gemm_phase(LAS unsigned char* lds, const Gemm g, const Sched& S, const Epi& E) {
;     ...
;             PG8_LDB(B0, 0, 0); PG8_SCHED; PG8_LDA(At, 0, 0); PG8_STAGE(PG8_SA(1, 1), a1 + hstep, voffA);
;             PG8_WAIT_L(8); PG8_BAR; PG8_WAIT_L(0); PG8_MMA(0, 0, At, B0); PG8_BAR; PG8_SCHED;
;             PG8_LDB(B1, 0, 1); PG8_STAGE(PG8_SB(0, 0), b2, voffB);
;             PG8_BAR; PG8_WAIT_L(0); PG8_MMA(0, 1, At, B1); PG8_BAR;
;             PG8_LDA(At, 0, 1); PG8_STAGE(PG8_SA(0, 0), a2, voffA);
;             PG8_BAR; PG8_WAIT_L(0); PG8_MMA(1, 0, At, B0); PG8_BAR; PG8_SCHED;
;             PG8_STAGE(PG8_SB(0, 1), b2 + hstep, voffB);
;             PG8_WAIT_V(6); PG8_BAR; PG8_MMA(1, 1, At, B1); PG8_BAR;
.LBB0_213:
	s_add_u32 s20, s16, 0xfff80080
	s_addc_u32 s21, s17, -1
	s_add_i32 s45, 0, 0x10000
	ds_read_b128 v[144:147], v129
	ds_read_b128 v[160:163], v129 offset:1024
	ds_read_b128 v[164:167], v129 offset:2048
	ds_read_b128 v[168:171], v129 offset:3072
	s_cmp_eq_u32 s44, 28
	s_cselect_b32 s23, s11, s21
	s_cselect_b32 s22, s40, s20
	s_cselect_b32 s21, s7, s43
	s_cselect_b32 s20, s41, s42
	s_add_i32 m0, s30, 0xc000
	ds_read_b128 v[172:175], v143
	ds_read_b128 v[200:203], v143 offset:1024
	ds_read_b128 v[204:207], v143 offset:2048
	ds_read_b128 v[208:211], v143 offset:3072
	ds_read_b128 v[212:215], v143 offset:4096
	ds_read_b128 v[216:219], v143 offset:5120
	ds_read_b128 v[220:223], v143 offset:6144
	ds_read_b128 v[224:227], v143 offset:7168
	global_load_lds_dwordx4 v134, s[16:17]
	s_add_i32 m0, s30, 0xe000
	s_nop 0
	global_load_lds_dwordx4 v136, s[16:17]
	s_waitcnt lgkmcnt(8)
	s_barrier
	s_waitcnt lgkmcnt(0)
	v_mfma_f32_16x16x32_bf16 v[124:127], v[144:147], v[172:175], v[124:127]
	v_mfma_f32_16x16x32_bf16 v[116:119], v[164:167], v[172:175], v[116:119]
	v_mfma_f32_16x16x32_bf16 v[108:111], v[144:147], v[204:207], v[108:111]
	v_mfma_f32_16x16x32_bf16 v[100:103], v[164:167], v[204:207], v[100:103]
	v_mfma_f32_16x16x32_bf16 v[92:95], v[144:147], v[212:215], v[92:95]
	v_mfma_f32_16x16x32_bf16 v[84:87], v[164:167], v[212:215], v[84:87]
	v_mfma_f32_16x16x32_bf16 v[76:79], v[144:147], v[220:223], v[76:79]
	v_mfma_f32_16x16x32_bf16 v[68:71], v[164:167], v[220:223], v[68:71]
	v_mfma_f32_16x16x32_bf16 v[124:127], v[160:163], v[200:203], v[124:127]
	v_mfma_f32_16x16x32_bf16 v[116:119], v[168:171], v[200:203], v[116:119]
	v_mfma_f32_16x16x32_bf16 v[108:111], v[160:163], v[208:211], v[108:111]
	v_mfma_f32_16x16x32_bf16 v[100:103], v[168:171], v[208:211], v[100:103]
	v_mfma_f32_16x16x32_bf16 v[92:95], v[160:163], v[216:219], v[92:95]
	v_mfma_f32_16x16x32_bf16 v[84:87], v[168:171], v[216:219], v[84:87]
	v_mfma_f32_16x16x32_bf16 v[76:79], v[160:163], v[224:227], v[76:79]
	v_mfma_f32_16x16x32_bf16 v[68:71], v[168:171], v[224:227], v[68:71]
	s_barrier
	s_add_i32 s48, 0, 0x14000
	s_add_i32 s45, s45, s29
	ds_read_b128 v[228:231], v129 offset:16384
	ds_read_b128 v[232:235], v129 offset:17408
	ds_read_b128 v[236:239], v129 offset:18432
	ds_read_b128 v[240:243], v129 offset:19456
	s_add_u32 s84, s20, 0x80
	s_addc_u32 s85, s21, 0
	s_mov_b32 m0, s45
	s_nop 0
	global_load_lds_dwordx4 v148, s[20:21]
	s_add_i32 m0, s45, 0x2000
	s_nop 0
	global_load_lds_dwordx4 v128, s[20:21]
	s_barrier
	s_waitcnt lgkmcnt(0)
	v_mfma_f32_16x16x32_bf16 v[120:123], v[228:231], v[172:175], v[120:123]
	v_mfma_f32_16x16x32_bf16 v[112:115], v[236:239], v[172:175], v[112:115]
	v_mfma_f32_16x16x32_bf16 v[104:107], v[228:231], v[204:207], v[104:107]
	v_mfma_f32_16x16x32_bf16 v[96:99], v[236:239], v[204:207], v[96:99]
	v_mfma_f32_16x16x32_bf16 v[88:91], v[228:231], v[212:215], v[88:91]
	v_mfma_f32_16x16x32_bf16 v[80:83], v[236:239], v[212:215], v[80:83]
	v_mfma_f32_16x16x32_bf16 v[72:75], v[228:231], v[220:223], v[72:75]
	v_mfma_f32_16x16x32_bf16 v[64:67], v[236:239], v[220:223], v[64:67]
	v_mfma_f32_16x16x32_bf16 v[120:123], v[232:235], v[200:203], v[120:123]
	v_mfma_f32_16x16x32_bf16 v[112:115], v[240:243], v[200:203], v[112:115]
	v_mfma_f32_16x16x32_bf16 v[104:107], v[232:235], v[208:211], v[104:107]
	v_mfma_f32_16x16x32_bf16 v[96:99], v[240:243], v[208:211], v[96:99]
	v_mfma_f32_16x16x32_bf16 v[88:91], v[232:235], v[216:219], v[88:91]
	v_mfma_f32_16x16x32_bf16 v[80:83], v[240:243], v[216:219], v[80:83]
	v_mfma_f32_16x16x32_bf16 v[72:75], v[232:235], v[224:227], v[72:75]
	v_mfma_f32_16x16x32_bf16 v[64:67], v[240:243], v[224:227], v[64:67]
	s_mov_b32 m0, s30
	s_add_u32 s86, s22, 0x80
	s_addc_u32 s87, s23, 0
	s_barrier
	ds_read_b128 v[172:175], v143 offset:16384
	ds_read_b128 v[200:203], v143 offset:17408
	ds_read_b128 v[204:207], v143 offset:18432
	ds_read_b128 v[208:211], v143 offset:19456
	ds_read_b128 v[212:215], v143 offset:20480
	ds_read_b128 v[216:219], v143 offset:21504
	ds_read_b128 v[220:223], v143 offset:22528
	ds_read_b128 v[224:227], v143 offset:23552
	global_load_lds_dwordx4 v132, s[22:23]
	s_mov_b32 m0, s31
	s_nop 0
	global_load_lds_dwordx4 v130, s[22:23]
	s_barrier
	s_waitcnt lgkmcnt(0)
	v_mfma_f32_16x16x32_bf16 v[60:63], v[144:147], v[172:175], v[60:63]
	v_mfma_f32_16x16x32_bf16 v[52:55], v[164:167], v[172:175], v[52:55]
	v_mfma_f32_16x16x32_bf16 v[44:47], v[144:147], v[204:207], v[44:47]
	v_mfma_f32_16x16x32_bf16 v[36:39], v[164:167], v[204:207], v[36:39]
	v_mfma_f32_16x16x32_bf16 v[28:31], v[144:147], v[212:215], v[28:31]
	v_mfma_f32_16x16x32_bf16 v[20:23], v[164:167], v[212:215], v[20:23]
	v_mfma_f32_16x16x32_bf16 v[12:15], v[144:147], v[220:223], v[12:15]
	v_mfma_f32_16x16x32_bf16 v[4:7], v[164:167], v[220:223], v[4:7]
	v_mfma_f32_16x16x32_bf16 v[60:63], v[160:163], v[200:203], v[60:63]
	v_mfma_f32_16x16x32_bf16 v[52:55], v[168:171], v[200:203], v[52:55]
	v_mfma_f32_16x16x32_bf16 v[44:47], v[160:163], v[208:211], v[44:47]
	v_mfma_f32_16x16x32_bf16 v[36:39], v[168:171], v[208:211], v[36:39]
	v_mfma_f32_16x16x32_bf16 v[28:31], v[160:163], v[216:219], v[28:31]
	v_mfma_f32_16x16x32_bf16 v[20:23], v[168:171], v[216:219], v[20:23]
	v_mfma_f32_16x16x32_bf16 v[12:15], v[160:163], v[224:227], v[12:15]
	v_mfma_f32_16x16x32_bf16 v[4:7], v[168:171], v[224:227], v[4:7]
	s_barrier
	s_add_u32 s46, s20, 0x80000
	s_addc_u32 s47, s21, 0
	s_add_i32 s45, s48, s29
	s_mov_b32 m0, s45
	s_nop 0
	global_load_lds_dwordx4 v148, s[46:47]
	s_add_i32 m0, s45, 0x2000
	s_nop 0
	global_load_lds_dwordx4 v128, s[46:47]
	s_waitcnt vmcnt(6)
	s_barrier
; #define PG8_STAGE(bufoff, gbase, voff) do { _Pragma("unroll") for (int _i = 0; _i < 2; ++_i) \
;         __builtin_amdgcn_global_load_lds((const unsigned*)((const char*)(gbase) + (voff)[_i]), (LAS unsigned*)(lds + (bufoff) + ldsw + _i * 8192), 16, 0, 0); } while (0)
; #define PG8_LDA(dst, b, h) do { _Pragma("unroll") for (int m = 0; m < 4; ++m) _Pragma("unroll") for (int k = 0; k < 2; ++k) dst[m][k] = *(const LAS bf16x8*)(lds + PG8_SA(b, h) + aoff + m * 2048 + k * 1024); } while (0)
; #define PG8_LDB(dst, b, h) do { _Pragma("unroll") for (int n = 0; n < 2; ++n) _Pragma("unroll") for (int k = 0; k < 2; ++k) dst[n][k] = *(const LAS bf16x8*)(lds + PG8_SB(b, h) + boff + n * 2048 + k * 1024); } while (0)
; #define PG8_MMA(ai, bj, At, Bt) do { __builtin_amdgcn_s_setprio(1); _Pragma("unroll") for (int m = 0; m < 4; ++m) _Pragma("unroll") for (int n = 0; n < 2; ++n) _Pragma("unroll") for (int k = 0; k < 2; ++k) \
;         acc[ai][bj][m][n] = __builtin_amdgcn_mfma_f32_16x16x32_bf16(Bt[n][k], At[m][k], acc[ai][bj][m][n], 0, 0, 0); __builtin_amdgcn_s_setprio(0); } while (0)
; #define PG8_WAIT_V(n) asm volatile("s_waitcnt vmcnt(" #n ")" ::: "memory")
; #define PG8_WAIT_L(n) asm volatile("s_waitcnt lgkmcnt(" #n ")" ::: "memory")
; #define PG8_BAR __builtin_amdgcn_s_barrier()
; #define PG8_SCHED __builtin_amdgcn_sched_barrier(0)
; template <class Epi, class Sched>
; __device__ __forceinline__ void gemm_phase(LAS unsigned char* lds, const Gemm g, const Sched& S, const Epi& E) {
;     ...
;             PG8_WAIT_V(6); PG8_BAR; PG8_MMA(1, 1, At, B1); PG8_BAR;
;             PG8_LDB(B0, 1, 0); PG8_SCHED; PG8_LDA(At, 1, 0); PG8_STAGE(PG8_SA(0, 1), a2 + hstep, voffA);
;             PG8_WAIT_L(8); PG8_BAR; PG8_WAIT_L(0); PG8_MMA(0, 0, At, B0); PG8_BAR; PG8_SCHED;
;             PG8_LDB(B1, 1, 1); PG8_STAGE(PG8_SB(1, 0), b3, voffB);
;             PG8_BAR; PG8_WAIT_L(0); PG8_MMA(0, 1, At, B1); PG8_BAR;
;             PG8_LDA(At, 1, 1); PG8_STAGE(PG8_SA(1, 0), a3, voffA);
;             PG8_BAR; PG8_WAIT_L(0); PG8_MMA(1, 0, At, B0); PG8_BAR; PG8_SCHED;
	v_mfma_f32_16x16x32_bf16 v[56:59], v[228:231], v[172:175], v[56:59]
	v_mfma_f32_16x16x32_bf16 v[48:51], v[236:239], v[172:175], v[48:51]
	v_mfma_f32_16x16x32_bf16 v[40:43], v[228:231], v[204:207], v[40:43]
	v_mfma_f32_16x16x32_bf16 v[32:35], v[236:239], v[204:207], v[32:35]
	v_mfma_f32_16x16x32_bf16 v[24:27], v[228:231], v[212:215], v[24:27]
	v_mfma_f32_16x16x32_bf16 v[16:19], v[236:239], v[212:215], v[16:19]
	v_mfma_f32_16x16x32_bf16 v[8:11], v[228:231], v[220:223], v[8:11]
	v_mfma_f32_16x16x32_bf16 v[0:3], v[236:239], v[220:223], v[0:3]
	v_mfma_f32_16x16x32_bf16 v[56:59], v[232:235], v[200:203], v[56:59]
	v_mfma_f32_16x16x32_bf16 v[48:51], v[240:243], v[200:203], v[48:51]
	v_mfma_f32_16x16x32_bf16 v[40:43], v[232:235], v[208:211], v[40:43]
	v_mfma_f32_16x16x32_bf16 v[32:35], v[240:243], v[208:211], v[32:35]
	v_mfma_f32_16x16x32_bf16 v[24:27], v[232:235], v[216:219], v[24:27]
	v_mfma_f32_16x16x32_bf16 v[16:19], v[240:243], v[216:219], v[16:19]
	v_mfma_f32_16x16x32_bf16 v[8:11], v[232:235], v[224:227], v[8:11]
	v_mfma_f32_16x16x32_bf16 v[0:3], v[240:243], v[224:227], v[0:3]
	s_add_i32 s45, 0, 0x18000
	s_barrier
	ds_read_b128 v[144:147], v129 offset:32768
	ds_read_b128 v[160:163], v129 offset:33792
	ds_read_b128 v[164:167], v129 offset:34816
	ds_read_b128 v[168:171], v129 offset:35840
	s_add_u32 s22, s22, 0x80000
	s_addc_u32 s23, s23, 0
	s_mov_b32 m0, s33
	ds_read_b128 v[172:175], v143 offset:32768
	ds_read_b128 v[200:203], v143 offset:33792
	ds_read_b128 v[204:207], v143 offset:34816
	ds_read_b128 v[208:211], v143 offset:35840
	ds_read_b128 v[212:215], v143 offset:36864
	ds_read_b128 v[216:219], v143 offset:37888
	ds_read_b128 v[220:223], v143 offset:38912
	ds_read_b128 v[224:227], v143 offset:39936
	global_load_lds_dwordx4 v132, s[22:23]
	s_mov_b32 m0, s34
	s_nop 0
	global_load_lds_dwordx4 v130, s[22:23]
	s_waitcnt lgkmcnt(8)
	s_barrier
	s_waitcnt lgkmcnt(0)
	v_mfma_f32_16x16x32_bf16 v[124:127], v[144:147], v[172:175], v[124:127]
	v_mfma_f32_16x16x32_bf16 v[116:119], v[164:167], v[172:175], v[116:119]
	v_mfma_f32_16x16x32_bf16 v[108:111], v[144:147], v[204:207], v[108:111]
	v_mfma_f32_16x16x32_bf16 v[100:103], v[164:167], v[204:207], v[100:103]
	v_mfma_f32_16x16x32_bf16 v[92:95], v[144:147], v[212:215], v[92:95]
	v_mfma_f32_16x16x32_bf16 v[84:87], v[164:167], v[212:215], v[84:87]
	v_mfma_f32_16x16x32_bf16 v[76:79], v[144:147], v[220:223], v[76:79]
	v_mfma_f32_16x16x32_bf16 v[68:71], v[164:167], v[220:223], v[68:71]
	v_mfma_f32_16x16x32_bf16 v[124:127], v[160:163], v[200:203], v[124:127]
	v_mfma_f32_16x16x32_bf16 v[116:119], v[168:171], v[200:203], v[116:119]
	v_mfma_f32_16x16x32_bf16 v[108:111], v[160:163], v[208:211], v[108:111]
	v_mfma_f32_16x16x32_bf16 v[100:103], v[168:171], v[208:211], v[100:103]
	v_mfma_f32_16x16x32_bf16 v[92:95], v[160:163], v[216:219], v[92:95]
	v_mfma_f32_16x16x32_bf16 v[84:87], v[168:171], v[216:219], v[84:87]
	v_mfma_f32_16x16x32_bf16 v[76:79], v[160:163], v[224:227], v[76:79]
	v_mfma_f32_16x16x32_bf16 v[68:71], v[168:171], v[224:227], v[68:71]
	s_barrier
	s_add_i32 s22, 0, 0x1c000
	s_add_i32 s23, s45, s29
	s_mov_b32 m0, s23
	ds_read_b128 v[228:231], v129 offset:49152
	ds_read_b128 v[232:235], v129 offset:50176
	ds_read_b128 v[236:239], v129 offset:51200
	ds_read_b128 v[240:243], v129 offset:52224
	global_load_lds_dwordx4 v148, s[84:85]
	s_add_i32 m0, s23, 0x2000
	s_nop 0
	global_load_lds_dwordx4 v128, s[84:85]
	s_barrier
	s_waitcnt lgkmcnt(0)
	v_mfma_f32_16x16x32_bf16 v[120:123], v[228:231], v[172:175], v[120:123]
	v_mfma_f32_16x16x32_bf16 v[112:115], v[236:239], v[172:175], v[112:115]
	v_mfma_f32_16x16x32_bf16 v[104:107], v[228:231], v[204:207], v[104:107]
	v_mfma_f32_16x16x32_bf16 v[96:99], v[236:239], v[204:207], v[96:99]
	v_mfma_f32_16x16x32_bf16 v[88:91], v[228:231], v[212:215], v[88:91]
	v_mfma_f32_16x16x32_bf16 v[80:83], v[236:239], v[212:215], v[80:83]
	v_mfma_f32_16x16x32_bf16 v[72:75], v[228:231], v[220:223], v[72:75]
	v_mfma_f32_16x16x32_bf16 v[64:67], v[236:239], v[220:223], v[64:67]
	v_mfma_f32_16x16x32_bf16 v[120:123], v[232:235], v[200:203], v[120:123]
	v_mfma_f32_16x16x32_bf16 v[112:115], v[240:243], v[200:203], v[112:115]
	v_mfma_f32_16x16x32_bf16 v[104:107], v[232:235], v[208:211], v[104:107]
	v_mfma_f32_16x16x32_bf16 v[96:99], v[240:243], v[208:211], v[96:99]
	v_mfma_f32_16x16x32_bf16 v[88:91], v[232:235], v[216:219], v[88:91]
	v_mfma_f32_16x16x32_bf16 v[80:83], v[240:243], v[216:219], v[80:83]
	v_mfma_f32_16x16x32_bf16 v[72:75], v[232:235], v[224:227], v[72:75]
	v_mfma_f32_16x16x32_bf16 v[64:67], v[240:243], v[224:227], v[64:67]
	s_mov_b32 m0, s35
	s_barrier
	ds_read_b128 v[172:175], v143 offset:49152
	ds_read_b128 v[200:203], v143 offset:50176
	ds_read_b128 v[204:207], v143 offset:51200
	ds_read_b128 v[208:211], v143 offset:52224
	ds_read_b128 v[212:215], v143 offset:53248
	ds_read_b128 v[216:219], v143 offset:54272
	ds_read_b128 v[220:223], v143 offset:55296
	ds_read_b128 v[224:227], v143 offset:56320
	global_load_lds_dwordx4 v132, s[86:87]
	s_mov_b32 m0, s36
	s_nop 0
	global_load_lds_dwordx4 v130, s[86:87]
	s_barrier
	s_waitcnt lgkmcnt(0)
	v_mfma_f32_16x16x32_bf16 v[60:63], v[144:147], v[172:175], v[60:63]
	v_mfma_f32_16x16x32_bf16 v[52:55], v[164:167], v[172:175], v[52:55]
	v_mfma_f32_16x16x32_bf16 v[44:47], v[144:147], v[204:207], v[44:47]
	v_mfma_f32_16x16x32_bf16 v[36:39], v[164:167], v[204:207], v[36:39]
	v_mfma_f32_16x16x32_bf16 v[28:31], v[144:147], v[212:215], v[28:31]
	v_mfma_f32_16x16x32_bf16 v[20:23], v[164:167], v[212:215], v[20:23]
	v_mfma_f32_16x16x32_bf16 v[12:15], v[144:147], v[220:223], v[12:15]
	v_mfma_f32_16x16x32_bf16 v[4:7], v[164:167], v[220:223], v[4:7]
	v_mfma_f32_16x16x32_bf16 v[60:63], v[160:163], v[200:203], v[60:63]
	v_mfma_f32_16x16x32_bf16 v[52:55], v[168:171], v[200:203], v[52:55]
	v_mfma_f32_16x16x32_bf16 v[44:47], v[160:163], v[208:211], v[44:47]
	v_mfma_f32_16x16x32_bf16 v[36:39], v[168:171], v[208:211], v[36:39]
	v_mfma_f32_16x16x32_bf16 v[28:31], v[160:163], v[216:219], v[28:31]
	v_mfma_f32_16x16x32_bf16 v[20:23], v[168:171], v[216:219], v[20:23]
	v_mfma_f32_16x16x32_bf16 v[12:15], v[160:163], v[224:227], v[12:15]
	v_mfma_f32_16x16x32_bf16 v[4:7], v[168:171], v[224:227], v[4:7]
	s_barrier
; __device__ __forceinline__ unsigned cvt_pk_bf16(float lo, float hi) { unsigned r; asm("v_cvt_pk_bf16_f32 %0, %1, %2" : "=v"(r) : "v"(lo), "v"(hi)); return r; }
; #define PG8_STAGE(bufoff, gbase, voff) do { _Pragma("unroll") for (int _i = 0; _i < 2; ++_i) \
;         __builtin_amdgcn_global_load_lds((const unsigned*)((const char*)(gbase) + (voff)[_i]), (LAS unsigned*)(lds + (bufoff) + ldsw + _i * 8192), 16, 0, 0); } while (0)
; #define PG8_MMA(ai, bj, At, Bt) do { __builtin_amdgcn_s_setprio(1); _Pragma("unroll") for (int m = 0; m < 4; ++m) _Pragma("unroll") for (int n = 0; n < 2; ++n) _Pragma("unroll") for (int k = 0; k < 2; ++k) \
;         acc[ai][bj][m][n] = __builtin_amdgcn_mfma_f32_16x16x32_bf16(Bt[n][k], At[m][k], acc[ai][bj][m][n], 0, 0, 0); __builtin_amdgcn_s_setprio(0); } while (0)
; #define PG8_WAIT_V(n) asm volatile("s_waitcnt vmcnt(" #n ")" ::: "memory")
; #define PG8_WAIT_L(n) asm volatile("s_waitcnt lgkmcnt(" #n ")" ::: "memory")
; #define PG8_BAR __builtin_amdgcn_s_barrier()
;     __device__ __forceinline__ void operator()(const f32x4 (&acc)[2][2][4][2], const Unit& u, int wr, int wc, int fr, int fq) const {
;         const int row0 = u.pm * BM + wr * 64 + fr, col0 = u.pn * HALF + wc * 32 + 8 * fq;
; #pragma unroll
;         for (int ai = 0; ai < 2; ++ai)
; #pragma unroll
;             for (int m = 0; m < 4; ++m) { bf16_t* rowp = O + (size_t)(row0 + ai * HALF + m * 16) * ldc + col0;
;                 float h[8];
; #pragma unroll
;                 for (int n = 0; n < 2; ++n)
; #pragma unroll
;                     for (int j = 0; j < 4; ++j) { const float g = acc[ai][0][m][n][j], up = acc[ai][1][m][n][j];
;                         const float e = __builtin_amdgcn_exp2f(-1.4426950408889634f * g);
;                         h[n * 4 + j] = g * __builtin_amdgcn_rcpf(1.0f + e) * up; }
;                 u32x4 w; w.x = cvt_pk_bf16(h[0], h[1]); w.y = cvt_pk_bf16(h[2], h[3]); w.z = cvt_pk_bf16(h[4], h[5]); w.w = cvt_pk_bf16(h[6], h[7]);
;                 *(u32x4*)rowp = w; }
; template <class Epi, class Sched>
; __device__ __forceinline__ void gemm_phase(LAS unsigned char* lds, const Gemm g, const Sched& S, const Epi& E) {
;     ...
;             PG8_BAR; PG8_WAIT_L(0); PG8_MMA(1, 0, At, B0); PG8_BAR; PG8_SCHED;
;             PG8_STAGE(PG8_SB(1, 1), b3 + hstep, voffB);
;             PG8_WAIT_V(6); PG8_BAR; PG8_MMA(1, 1, At, B1); PG8_BAR;
	s_add_u32 s20, s20, 0x80080
	s_addc_u32 s21, s21, 0
	s_add_i32 s22, s22, s29
	s_mov_b32 m0, s22
	s_nop 0
	global_load_lds_dwordx4 v148, s[20:21]
	s_add_i32 m0, s22, 0x2000
	s_nop 0
	global_load_lds_dwordx4 v128, s[20:21]
	s_waitcnt vmcnt(6)
	s_barrier
	v_mfma_f32_16x16x32_bf16 v[56:59], v[228:231], v[172:175], v[56:59]
	v_mfma_f32_16x16x32_bf16 v[48:51], v[236:239], v[172:175], v[48:51]
	v_mfma_f32_16x16x32_bf16 v[40:43], v[228:231], v[204:207], v[40:43]
	v_mfma_f32_16x16x32_bf16 v[32:35], v[236:239], v[204:207], v[32:35]
	v_mfma_f32_16x16x32_bf16 v[24:27], v[228:231], v[212:215], v[24:27]
	v_mfma_f32_16x16x32_bf16 v[16:19], v[236:239], v[212:215], v[16:19]
	v_mfma_f32_16x16x32_bf16 v[8:11], v[228:231], v[220:223], v[8:11]
	v_mfma_f32_16x16x32_bf16 v[0:3], v[236:239], v[220:223], v[0:3]
	v_mfma_f32_16x16x32_bf16 v[56:59], v[232:235], v[200:203], v[56:59]
	v_mfma_f32_16x16x32_bf16 v[48:51], v[240:243], v[200:203], v[48:51]
	v_mfma_f32_16x16x32_bf16 v[40:43], v[232:235], v[208:211], v[40:43]
	v_mfma_f32_16x16x32_bf16 v[32:35], v[240:243], v[208:211], v[32:35]
	v_mfma_f32_16x16x32_bf16 v[24:27], v[232:235], v[216:219], v[24:27]
	v_mfma_f32_16x16x32_bf16 v[16:19], v[240:243], v[216:219], v[16:19]
	v_mfma_f32_16x16x32_bf16 v[8:11], v[232:235], v[224:227], v[8:11]
	v_mfma_f32_16x16x32_bf16 v[0:3], v[240:243], v[224:227], v[0:3]
	s_add_i32 s44, s44, 2
	s_add_u32 s16, s16, 0x100
	s_addc_u32 s17, s17, 0
	s_add_u32 s42, s42, 0x100
	s_addc_u32 s43, s43, 0
	s_cmp_gt_u32 s44, 29
	s_barrier
	s_cbranch_scc0 .LBB0_213
	v_mul_f32_e32 v145, 0xbfb8aa3b, v124
	v_exp_f32_e32 v145, v145
	v_lshl_or_b32 v146, s38, 7, v142
	v_lshl_add_u32 v144, s39, 8, v140
	v_ashrrev_i32_e32 v147, 31, v146
	v_add_f32_e32 v145, 1.0, v145
	v_rcp_f32_e32 v145, v145
	v_mov_b64_e32 v[138:139], s[4:5]
	s_movk_i32 s7, 0x2c00
	v_mad_i64_i32 v[160:161], s[16:17], v144, s7, v[138:139]
	v_mul_f32_e32 v124, v124, v145
	v_mul_f32_e32 v120, v120, v124
	v_mul_f32_e32 v124, 0xbfb8aa3b, v125
	v_exp_f32_e32 v124, v124
	s_and_b64 vcc, exec, s[0:1]
	s_mov_b32 s38, s6
	s_mov_b32 s39, s10
	v_add_f32_e32 v124, 1.0, v124
	v_rcp_f32_e32 v124, v124
	s_mov_b64 s[20:21], s[14:15]
	v_mul_f32_e32 v124, v125, v124
	v_mul_f32_e32 v121, v121, v124
	v_mul_f32_e32 v124, 0xbfb8aa3b, v126
	v_exp_f32_e32 v124, v124
	s_nop 0
	v_add_f32_e32 v124, 1.0, v124
	v_rcp_f32_e32 v124, v124
	s_nop 0
	v_mul_f32_e32 v124, v126, v124
	v_mul_f32_e32 v122, v122, v124
	v_mul_f32_e32 v124, 0xbfb8aa3b, v127
	v_exp_f32_e32 v124, v124
	s_nop 0
	v_add_f32_e32 v124, 1.0, v124
	v_rcp_f32_e32 v124, v124
	s_nop 0
	v_mul_f32_e32 v124, v127, v124
	v_mul_f32_e32 v123, v123, v124
	v_mul_f32_e32 v124, 0xbfb8aa3b, v116
	v_exp_f32_e32 v124, v124
	s_nop 0
	v_add_f32_e32 v124, 1.0, v124
	v_rcp_f32_e32 v124, v124
	s_nop 0
	v_mul_f32_e32 v116, v116, v124
	v_mul_f32_e32 v116, v112, v116
	v_mul_f32_e32 v112, 0xbfb8aa3b, v117
	v_exp_f32_e32 v112, v112
	s_nop 0
	v_add_f32_e32 v112, 1.0, v112
	v_rcp_f32_e32 v112, v112
	s_nop 0
	v_mul_f32_e32 v112, v117, v112
	v_mul_f32_e32 v117, v113, v112
	v_mul_f32_e32 v112, 0xbfb8aa3b, v118
	v_exp_f32_e32 v112, v112
	v_cvt_pk_bf16_f32 v116, v116, v117
	s_nop 0
	v_add_f32_e32 v112, 1.0, v112
	v_rcp_f32_e32 v112, v112
	s_nop 0
	v_mul_f32_e32 v112, v118, v112
	v_mul_f32_e32 v124, v114, v112
	v_mul_f32_e32 v112, 0xbfb8aa3b, v119
	v_exp_f32_e32 v112, v112
	v_cvt_pk_bf16_f32 v114, v120, v121
	s_nop 0
	v_add_f32_e32 v112, 1.0, v112
	v_rcp_f32_e32 v112, v112
	s_nop 0
	v_mul_f32_e32 v112, v119, v112
	v_mul_f32_e32 v125, v115, v112
	v_lshlrev_b64 v[112:113], 1, v[146:147]
	v_lshl_add_u64 v[118:119], v[160:161], 0, v[112:113]
	v_cvt_pk_bf16_f32 v115, v122, v123
	v_cvt_pk_bf16_f32 v117, v124, v125
	global_store_dwordx4 v[118:119], v[114:117], off
	s_nop 1
	v_mul_f32_e32 v116, 0xbfb8aa3b, v108
	v_exp_f32_e32 v116, v116
	v_or_b32_e32 v114, 16, v144
	v_mad_i64_i32 v[114:115], s[16:17], v114, s7, v[138:139]
	v_add_f32_e32 v116, 1.0, v116
	v_rcp_f32_e32 v116, v116
	s_nop 0
	v_mul_f32_e32 v108, v108, v116
	v_mul_f32_e32 v104, v104, v108
	v_mul_f32_e32 v108, 0xbfb8aa3b, v109
	v_exp_f32_e32 v108, v108
	s_nop 0
	v_add_f32_e32 v108, 1.0, v108
	v_rcp_f32_e32 v108, v108
	s_nop 0
	v_mul_f32_e32 v108, v109, v108
	v_mul_f32_e32 v105, v105, v108
	v_mul_f32_e32 v108, 0xbfb8aa3b, v110
	v_exp_f32_e32 v108, v108
	s_nop 0
	v_add_f32_e32 v108, 1.0, v108
	v_rcp_f32_e32 v108, v108
	s_nop 0
	v_mul_f32_e32 v108, v110, v108
	v_mul_f32_e32 v106, v106, v108
	v_mul_f32_e32 v108, 0xbfb8aa3b, v111
	v_exp_f32_e32 v108, v108
	s_nop 0
	v_add_f32_e32 v108, 1.0, v108
	v_rcp_f32_e32 v108, v108
	s_nop 0
	v_mul_f32_e32 v108, v111, v108
	v_mul_f32_e32 v107, v107, v108
	v_mul_f32_e32 v108, 0xbfb8aa3b, v100
	v_exp_f32_e32 v108, v108
	s_nop 0
	v_add_f32_e32 v108, 1.0, v108
	v_rcp_f32_e32 v108, v108
	s_nop 0
	v_mul_f32_e32 v100, v100, v108
	v_mul_f32_e32 v108, v96, v100
	v_mul_f32_e32 v96, 0xbfb8aa3b, v101
	v_exp_f32_e32 v96, v96
	s_nop 0
	v_add_f32_e32 v96, 1.0, v96
	v_rcp_f32_e32 v96, v96
	s_nop 0
	v_mul_f32_e32 v96, v101, v96
	v_mul_f32_e32 v109, v97, v96
	v_mul_f32_e32 v96, 0xbfb8aa3b, v102
	v_exp_f32_e32 v96, v96
	v_lshl_add_u64 v[100:101], v[114:115], 0, v[112:113]
	v_cvt_pk_bf16_f32 v97, v106, v107
	v_add_f32_e32 v96, 1.0, v96
	v_rcp_f32_e32 v96, v96
	s_nop 0
	v_mul_f32_e32 v96, v102, v96
	v_mul_f32_e32 v102, v98, v96
	v_mul_f32_e32 v96, 0xbfb8aa3b, v103
	v_exp_f32_e32 v96, v96
	v_cvt_pk_bf16_f32 v98, v108, v109
	s_nop 0
	v_add_f32_e32 v96, 1.0, v96
	v_rcp_f32_e32 v96, v96
	s_nop 0
	v_mul_f32_e32 v96, v103, v96
	v_mul_f32_e32 v99, v99, v96
	v_cvt_pk_bf16_f32 v96, v104, v105
	v_cvt_pk_bf16_f32 v99, v102, v99
	global_store_dwordx4 v[100:101], v[96:99], off
	s_nop 1
; __device__ __forceinline__ unsigned cvt_pk_bf16(float lo, float hi) { unsigned r; asm("v_cvt_pk_bf16_f32 %0, %1, %2" : "=v"(r) : "v"(lo), "v"(hi)); return r; }
;     __device__ __forceinline__ void operator()(const f32x4 (&acc)[2][2][4][2], const Unit& u, int wr, int wc, int fr, int fq) const {
;         const int row0 = u.pm * BM + wr * 64 + fr, col0 = u.pn * HALF + wc * 32 + 8 * fq;
; #pragma unroll
;         for (int ai = 0; ai < 2; ++ai)
; #pragma unroll
;             for (int m = 0; m < 4; ++m) { bf16_t* rowp = O + (size_t)(row0 + ai * HALF + m * 16) * ldc + col0;
;                 float h[8];
; #pragma unroll
;                 for (int n = 0; n < 2; ++n)
; #pragma unroll
;                     for (int j = 0; j < 4; ++j) { const float g = acc[ai][0][m][n][j], up = acc[ai][1][m][n][j];
;                         const float e = __builtin_amdgcn_exp2f(-1.4426950408889634f * g);
;                         h[n * 4 + j] = g * __builtin_amdgcn_rcpf(1.0f + e) * up; }
;                 u32x4 w; w.x = cvt_pk_bf16(h[0], h[1]); w.y = cvt_pk_bf16(h[2], h[3]); w.z = cvt_pk_bf16(h[4], h[5]); w.w = cvt_pk_bf16(h[6], h[7]);
;                 *(u32x4*)rowp = w; }
	v_mul_f32_e32 v98, 0xbfb8aa3b, v92
	v_exp_f32_e32 v98, v98
	v_or_b32_e32 v96, 32, v144
	v_mad_i64_i32 v[96:97], s[16:17], v96, s7, v[138:139]
	v_add_f32_e32 v98, 1.0, v98
	v_rcp_f32_e32 v98, v98
	s_nop 0
	v_mul_f32_e32 v92, v92, v98
	v_mul_f32_e32 v88, v88, v92
	v_mul_f32_e32 v92, 0xbfb8aa3b, v93
	v_exp_f32_e32 v92, v92
	s_nop 0
	v_add_f32_e32 v92, 1.0, v92
	v_rcp_f32_e32 v92, v92
	s_nop 0
	v_mul_f32_e32 v92, v93, v92
	v_mul_f32_e32 v89, v89, v92
	v_mul_f32_e32 v92, 0xbfb8aa3b, v94
	v_exp_f32_e32 v92, v92
	s_nop 0
	v_add_f32_e32 v92, 1.0, v92
	v_rcp_f32_e32 v92, v92
	s_nop 0
	v_mul_f32_e32 v92, v94, v92
	v_mul_f32_e32 v90, v90, v92
	v_mul_f32_e32 v92, 0xbfb8aa3b, v95
	v_exp_f32_e32 v92, v92
	s_nop 0
	v_add_f32_e32 v92, 1.0, v92
	v_rcp_f32_e32 v92, v92
	s_nop 0
	v_mul_f32_e32 v92, v95, v92
	v_mul_f32_e32 v91, v91, v92
	v_mul_f32_e32 v92, 0xbfb8aa3b, v84
	v_exp_f32_e32 v92, v92
	s_nop 0
	v_add_f32_e32 v92, 1.0, v92
	v_rcp_f32_e32 v92, v92
	s_nop 0
	v_mul_f32_e32 v84, v84, v92
	v_mul_f32_e32 v92, v80, v84
	v_mul_f32_e32 v80, 0xbfb8aa3b, v85
	v_exp_f32_e32 v80, v80
	s_nop 0
	v_add_f32_e32 v80, 1.0, v80
	v_rcp_f32_e32 v80, v80
	s_nop 0
	v_mul_f32_e32 v80, v85, v80
	v_mul_f32_e32 v93, v81, v80
	v_mul_f32_e32 v80, 0xbfb8aa3b, v86
	v_exp_f32_e32 v80, v80
	v_lshl_add_u64 v[84:85], v[96:97], 0, v[112:113]
	v_cvt_pk_bf16_f32 v81, v90, v91
	v_add_f32_e32 v80, 1.0, v80
	v_rcp_f32_e32 v80, v80
	s_nop 0
	v_mul_f32_e32 v80, v86, v80
	v_mul_f32_e32 v86, v82, v80
	v_mul_f32_e32 v80, 0xbfb8aa3b, v87
	v_exp_f32_e32 v80, v80
	v_cvt_pk_bf16_f32 v82, v92, v93
	s_nop 0
	v_add_f32_e32 v80, 1.0, v80
	v_rcp_f32_e32 v80, v80
	s_nop 0
	v_mul_f32_e32 v80, v87, v80
	v_mul_f32_e32 v83, v83, v80
	v_cvt_pk_bf16_f32 v80, v88, v89
	v_cvt_pk_bf16_f32 v83, v86, v83
	global_store_dwordx4 v[84:85], v[80:83], off
	s_nop 1
	v_mul_f32_e32 v82, 0xbfb8aa3b, v76
	v_exp_f32_e32 v82, v82
	v_or_b32_e32 v80, 48, v144
	v_mad_i64_i32 v[80:81], s[16:17], v80, s7, v[138:139]
	v_add_f32_e32 v82, 1.0, v82
	v_rcp_f32_e32 v82, v82
	s_nop 0
	v_mul_f32_e32 v76, v76, v82
	v_mul_f32_e32 v72, v72, v76
	v_mul_f32_e32 v76, 0xbfb8aa3b, v77
	v_exp_f32_e32 v76, v76
	s_nop 0
	v_add_f32_e32 v76, 1.0, v76
	v_rcp_f32_e32 v76, v76
	s_nop 0
	v_mul_f32_e32 v76, v77, v76
	v_mul_f32_e32 v73, v73, v76
	v_mul_f32_e32 v76, 0xbfb8aa3b, v78
	v_exp_f32_e32 v76, v76
	s_nop 0
	v_add_f32_e32 v76, 1.0, v76
	v_rcp_f32_e32 v76, v76
	s_nop 0
	v_mul_f32_e32 v76, v78, v76
	v_mul_f32_e32 v74, v74, v76
	v_mul_f32_e32 v76, 0xbfb8aa3b, v79
	v_exp_f32_e32 v76, v76
	s_nop 0
	v_add_f32_e32 v76, 1.0, v76
	v_rcp_f32_e32 v76, v76
	s_nop 0
	v_mul_f32_e32 v76, v79, v76
	v_mul_f32_e32 v75, v75, v76
	v_mul_f32_e32 v76, 0xbfb8aa3b, v68
	v_exp_f32_e32 v76, v76
	s_nop 0
	v_add_f32_e32 v76, 1.0, v76
	v_rcp_f32_e32 v76, v76
	s_nop 0
	v_mul_f32_e32 v68, v68, v76
	v_mul_f32_e32 v76, v64, v68
	v_mul_f32_e32 v64, 0xbfb8aa3b, v69
	v_exp_f32_e32 v64, v64
	s_nop 0
	v_add_f32_e32 v64, 1.0, v64
	v_rcp_f32_e32 v64, v64
	s_nop 0
	v_mul_f32_e32 v64, v69, v64
	v_mul_f32_e32 v77, v65, v64
	v_mul_f32_e32 v64, 0xbfb8aa3b, v70
	v_exp_f32_e32 v64, v64
	v_lshl_add_u64 v[68:69], v[80:81], 0, v[112:113]
	v_cvt_pk_bf16_f32 v65, v74, v75
	v_add_f32_e32 v64, 1.0, v64
	v_rcp_f32_e32 v64, v64
	s_nop 0
	v_mul_f32_e32 v64, v70, v64
	v_mul_f32_e32 v70, v66, v64
	v_mul_f32_e32 v64, 0xbfb8aa3b, v71
	v_exp_f32_e32 v64, v64
	v_cvt_pk_bf16_f32 v66, v76, v77
	s_nop 0
	v_add_f32_e32 v64, 1.0, v64
	v_rcp_f32_e32 v64, v64
	s_nop 0
	v_mul_f32_e32 v64, v71, v64
	v_mul_f32_e32 v67, v67, v64
	v_cvt_pk_bf16_f32 v64, v72, v73
	v_cvt_pk_bf16_f32 v67, v70, v67
	global_store_dwordx4 v[68:69], v[64:67], off
	s_nop 1
	v_mul_f32_e32 v66, 0xbfb8aa3b, v60
	v_exp_f32_e32 v66, v66
	v_add_u32_e32 v64, 0x80, v144
	v_mad_i64_i32 v[64:65], s[16:17], v64, s7, v[138:139]
	v_add_f32_e32 v66, 1.0, v66
	v_rcp_f32_e32 v66, v66
	s_nop 0
	v_mul_f32_e32 v60, v60, v66
	v_mul_f32_e32 v56, v56, v60
	v_mul_f32_e32 v60, 0xbfb8aa3b, v61
	v_exp_f32_e32 v60, v60
	s_nop 0
	v_add_f32_e32 v60, 1.0, v60
	v_rcp_f32_e32 v60, v60
	s_nop 0
	v_mul_f32_e32 v60, v61, v60
	v_mul_f32_e32 v57, v57, v60
	v_mul_f32_e32 v60, 0xbfb8aa3b, v62
	v_exp_f32_e32 v60, v60
	s_nop 0
	v_add_f32_e32 v60, 1.0, v60
	v_rcp_f32_e32 v60, v60
	s_nop 0
	v_mul_f32_e32 v60, v62, v60
	v_mul_f32_e32 v58, v58, v60
	v_mul_f32_e32 v60, 0xbfb8aa3b, v63
	v_exp_f32_e32 v60, v60
	s_nop 0
	v_add_f32_e32 v60, 1.0, v60
	v_rcp_f32_e32 v60, v60
	s_nop 0
	v_mul_f32_e32 v60, v63, v60
	v_mul_f32_e32 v59, v59, v60
	v_mul_f32_e32 v60, 0xbfb8aa3b, v52
	v_exp_f32_e32 v60, v60
	s_nop 0
	v_add_f32_e32 v60, 1.0, v60
	v_rcp_f32_e32 v60, v60
	s_nop 0
	v_mul_f32_e32 v52, v52, v60
	v_mul_f32_e32 v60, v48, v52
	v_mul_f32_e32 v48, 0xbfb8aa3b, v53
	v_exp_f32_e32 v48, v48
	s_nop 0
	v_add_f32_e32 v48, 1.0, v48
	v_rcp_f32_e32 v48, v48
	s_nop 0
	v_mul_f32_e32 v48, v53, v48
	v_mul_f32_e32 v61, v49, v48
	v_mul_f32_e32 v48, 0xbfb8aa3b, v54
	v_exp_f32_e32 v48, v48
	v_lshl_add_u64 v[52:53], v[64:65], 0, v[112:113]
	v_cvt_pk_bf16_f32 v49, v58, v59
	v_add_f32_e32 v48, 1.0, v48
	v_rcp_f32_e32 v48, v48
	s_nop 0
	v_mul_f32_e32 v48, v54, v48
	v_mul_f32_e32 v54, v50, v48
	v_mul_f32_e32 v48, 0xbfb8aa3b, v55
	v_exp_f32_e32 v48, v48
	v_cvt_pk_bf16_f32 v50, v60, v61
	s_nop 0
	v_add_f32_e32 v48, 1.0, v48
	v_rcp_f32_e32 v48, v48
	s_nop 0
	v_mul_f32_e32 v48, v55, v48
	v_mul_f32_e32 v51, v51, v48
	v_cvt_pk_bf16_f32 v48, v56, v57
	v_cvt_pk_bf16_f32 v51, v54, v51
	global_store_dwordx4 v[52:53], v[48:51], off
	s_nop 1
	v_mul_f32_e32 v50, 0xbfb8aa3b, v44
; __device__ __forceinline__ unsigned cvt_pk_bf16(float lo, float hi) { unsigned r; asm("v_cvt_pk_bf16_f32 %0, %1, %2" : "=v"(r) : "v"(lo), "v"(hi)); return r; }
; #define PG8_WAIT_V(n) asm volatile("s_waitcnt vmcnt(" #n ")" ::: "memory")
; #define PG8_BAR __builtin_amdgcn_s_barrier()
;     __device__ __forceinline__ void operator()(const f32x4 (&acc)[2][2][4][2], const Unit& u, int wr, int wc, int fr, int fq) const {
;         const int row0 = u.pm * BM + wr * 64 + fr, col0 = u.pn * HALF + wc * 32 + 8 * fq;
; #pragma unroll
;         for (int ai = 0; ai < 2; ++ai)
; #pragma unroll
;             for (int m = 0; m < 4; ++m) { bf16_t* rowp = O + (size_t)(row0 + ai * HALF + m * 16) * ldc + col0;
;                 float h[8];
; #pragma unroll
;                 for (int n = 0; n < 2; ++n)
; #pragma unroll
;                     for (int j = 0; j < 4; ++j) { const float g = acc[ai][0][m][n][j], up = acc[ai][1][m][n][j];
;                         const float e = __builtin_amdgcn_exp2f(-1.4426950408889634f * g);
;                         h[n * 4 + j] = g * __builtin_amdgcn_rcpf(1.0f + e) * up; }
;                 u32x4 w; w.x = cvt_pk_bf16(h[0], h[1]); w.y = cvt_pk_bf16(h[2], h[3]); w.z = cvt_pk_bf16(h[4], h[5]); w.w = cvt_pk_bf16(h[6], h[7]);
;                 *(u32x4*)rowp = w; }
; template <class Epi, class Sched>
; __device__ __forceinline__ void gemm_phase(LAS unsigned char* lds, const Gemm g, const Sched& S, const Epi& E) {
;     ...
;     PG8_WAIT_V(0);
;     if (wr == 0) PG8_BAR;
;     PG8_BAR;
	v_exp_f32_e32 v50, v50
	v_add_u32_e32 v48, 0x90, v144
	v_mad_i64_i32 v[48:49], s[16:17], v48, s7, v[138:139]
	v_add_f32_e32 v50, 1.0, v50
	v_rcp_f32_e32 v50, v50
	s_nop 0
	v_mul_f32_e32 v44, v44, v50
	v_mul_f32_e32 v40, v40, v44
	v_mul_f32_e32 v44, 0xbfb8aa3b, v45
	v_exp_f32_e32 v44, v44
	s_nop 0
	v_add_f32_e32 v44, 1.0, v44
	v_rcp_f32_e32 v44, v44
	s_nop 0
	v_mul_f32_e32 v44, v45, v44
	v_mul_f32_e32 v41, v41, v44
	v_mul_f32_e32 v44, 0xbfb8aa3b, v46
	v_exp_f32_e32 v44, v44
	s_nop 0
	v_add_f32_e32 v44, 1.0, v44
	v_rcp_f32_e32 v44, v44
	s_nop 0
	v_mul_f32_e32 v44, v46, v44
	v_mul_f32_e32 v42, v42, v44
	v_mul_f32_e32 v44, 0xbfb8aa3b, v47
	v_exp_f32_e32 v44, v44
	s_nop 0
	v_add_f32_e32 v44, 1.0, v44
	v_rcp_f32_e32 v44, v44
	s_nop 0
	v_mul_f32_e32 v44, v47, v44
	v_mul_f32_e32 v43, v43, v44
	v_mul_f32_e32 v44, 0xbfb8aa3b, v36
	v_exp_f32_e32 v44, v44
	s_nop 0
	v_add_f32_e32 v44, 1.0, v44
	v_rcp_f32_e32 v44, v44
	s_nop 0
	v_mul_f32_e32 v36, v36, v44
	v_mul_f32_e32 v44, v32, v36
	v_mul_f32_e32 v32, 0xbfb8aa3b, v37
	v_exp_f32_e32 v32, v32
	s_nop 0
	v_add_f32_e32 v32, 1.0, v32
	v_rcp_f32_e32 v32, v32
	s_nop 0
	v_mul_f32_e32 v32, v37, v32
	v_mul_f32_e32 v45, v33, v32
	v_mul_f32_e32 v32, 0xbfb8aa3b, v38
	v_exp_f32_e32 v32, v32
	v_lshl_add_u64 v[36:37], v[48:49], 0, v[112:113]
	v_cvt_pk_bf16_f32 v33, v42, v43
	v_add_f32_e32 v32, 1.0, v32
	v_rcp_f32_e32 v32, v32
	s_nop 0
	v_mul_f32_e32 v32, v38, v32
	v_mul_f32_e32 v38, v34, v32
	v_mul_f32_e32 v32, 0xbfb8aa3b, v39
	v_exp_f32_e32 v32, v32
	v_cvt_pk_bf16_f32 v34, v44, v45
	s_nop 0
	v_add_f32_e32 v32, 1.0, v32
	v_rcp_f32_e32 v32, v32
	s_nop 0
	v_mul_f32_e32 v32, v39, v32
	v_mul_f32_e32 v35, v35, v32
	v_cvt_pk_bf16_f32 v32, v40, v41
	v_cvt_pk_bf16_f32 v35, v38, v35
	global_store_dwordx4 v[36:37], v[32:35], off
	s_nop 1
	v_mul_f32_e32 v34, 0xbfb8aa3b, v28
	v_exp_f32_e32 v34, v34
	v_add_u32_e32 v32, 0xa0, v144
	v_mad_i64_i32 v[32:33], s[16:17], v32, s7, v[138:139]
	v_add_f32_e32 v34, 1.0, v34
	v_rcp_f32_e32 v34, v34
	s_nop 0
	v_mul_f32_e32 v28, v28, v34
	v_mul_f32_e32 v24, v24, v28
	v_mul_f32_e32 v28, 0xbfb8aa3b, v29
	v_exp_f32_e32 v28, v28
	s_nop 0
	v_add_f32_e32 v28, 1.0, v28
	v_rcp_f32_e32 v28, v28
	s_nop 0
	v_mul_f32_e32 v28, v29, v28
	v_mul_f32_e32 v25, v25, v28
	v_mul_f32_e32 v28, 0xbfb8aa3b, v30
	v_exp_f32_e32 v28, v28
	s_nop 0
	v_add_f32_e32 v28, 1.0, v28
	v_rcp_f32_e32 v28, v28
	s_nop 0
	v_mul_f32_e32 v28, v30, v28
	v_mul_f32_e32 v26, v26, v28
	v_mul_f32_e32 v28, 0xbfb8aa3b, v31
	v_exp_f32_e32 v28, v28
	s_nop 0
	v_add_f32_e32 v28, 1.0, v28
	v_rcp_f32_e32 v28, v28
	s_nop 0
	v_mul_f32_e32 v28, v31, v28
	v_mul_f32_e32 v27, v27, v28
	v_mul_f32_e32 v28, 0xbfb8aa3b, v20
	v_exp_f32_e32 v28, v28
	s_nop 0
	v_add_f32_e32 v28, 1.0, v28
	v_rcp_f32_e32 v28, v28
	s_nop 0
	v_mul_f32_e32 v20, v20, v28
	v_mul_f32_e32 v28, v16, v20
	v_mul_f32_e32 v16, 0xbfb8aa3b, v21
	v_exp_f32_e32 v16, v16
	s_nop 0
	v_add_f32_e32 v16, 1.0, v16
	v_rcp_f32_e32 v16, v16
	s_nop 0
	v_mul_f32_e32 v16, v21, v16
	v_mul_f32_e32 v29, v17, v16
	v_mul_f32_e32 v16, 0xbfb8aa3b, v22
	v_exp_f32_e32 v16, v16
	v_lshl_add_u64 v[20:21], v[32:33], 0, v[112:113]
	v_cvt_pk_bf16_f32 v17, v26, v27
	v_add_f32_e32 v16, 1.0, v16
	v_rcp_f32_e32 v16, v16
	s_nop 0
	v_mul_f32_e32 v16, v22, v16
	v_mul_f32_e32 v22, v18, v16
	v_mul_f32_e32 v16, 0xbfb8aa3b, v23
	v_exp_f32_e32 v16, v16
	v_cvt_pk_bf16_f32 v18, v28, v29
	s_nop 0
	v_add_f32_e32 v16, 1.0, v16
	v_rcp_f32_e32 v16, v16
	s_nop 0
	v_mul_f32_e32 v16, v23, v16
	v_mul_f32_e32 v19, v19, v16
	v_cvt_pk_bf16_f32 v16, v24, v25
	v_cvt_pk_bf16_f32 v19, v22, v19
	global_store_dwordx4 v[20:21], v[16:19], off
	s_nop 1
	v_mul_f32_e32 v18, 0xbfb8aa3b, v12
	v_exp_f32_e32 v18, v18
	v_add_u32_e32 v16, 0xb0, v144
	v_mad_i64_i32 v[16:17], s[16:17], v16, s7, v[138:139]
	v_add_f32_e32 v18, 1.0, v18
	v_rcp_f32_e32 v18, v18
	s_mov_b64 s[16:17], s[12:13]
	v_mul_f32_e32 v12, v12, v18
	v_mul_f32_e32 v8, v8, v12
	v_mul_f32_e32 v12, 0xbfb8aa3b, v13
	v_exp_f32_e32 v12, v12
	s_nop 0
	v_add_f32_e32 v12, 1.0, v12
	v_rcp_f32_e32 v12, v12
	s_nop 0
	v_mul_f32_e32 v12, v13, v12
	v_mul_f32_e32 v9, v9, v12
	v_mul_f32_e32 v12, 0xbfb8aa3b, v14
	v_exp_f32_e32 v12, v12
	s_nop 0
	v_add_f32_e32 v12, 1.0, v12
	v_rcp_f32_e32 v12, v12
	s_nop 0
	v_mul_f32_e32 v12, v14, v12
	v_mul_f32_e32 v10, v10, v12
	v_mul_f32_e32 v12, 0xbfb8aa3b, v15
	v_exp_f32_e32 v12, v12
	s_nop 0
	v_add_f32_e32 v12, 1.0, v12
	v_rcp_f32_e32 v12, v12
	s_nop 0
	v_mul_f32_e32 v12, v15, v12
	v_mul_f32_e32 v11, v11, v12
	v_mul_f32_e32 v12, 0xbfb8aa3b, v4
	v_exp_f32_e32 v12, v12
	s_nop 0
	v_add_f32_e32 v12, 1.0, v12
	v_rcp_f32_e32 v12, v12
	s_nop 0
	v_mul_f32_e32 v4, v4, v12
	v_mul_f32_e32 v12, v0, v4
	v_mul_f32_e32 v0, 0xbfb8aa3b, v5
	v_exp_f32_e32 v0, v0
	s_nop 0
	v_add_f32_e32 v0, 1.0, v0
	v_rcp_f32_e32 v0, v0
	s_nop 0
	v_mul_f32_e32 v0, v5, v0
	v_mul_f32_e32 v13, v1, v0
	v_mul_f32_e32 v0, 0xbfb8aa3b, v6
	v_exp_f32_e32 v0, v0
	v_lshl_add_u64 v[4:5], v[16:17], 0, v[112:113]
	v_cvt_pk_bf16_f32 v1, v10, v11
	v_add_f32_e32 v0, 1.0, v0
	v_rcp_f32_e32 v0, v0
	s_nop 0
	v_mul_f32_e32 v0, v6, v0
	v_mul_f32_e32 v6, v2, v0
	v_mul_f32_e32 v0, 0xbfb8aa3b, v7
	v_exp_f32_e32 v0, v0
	v_cvt_pk_bf16_f32 v2, v12, v13
	s_nop 0
	v_add_f32_e32 v0, 1.0, v0
	v_rcp_f32_e32 v0, v0
	s_nop 0
	v_mul_f32_e32 v0, v7, v0
	v_mul_f32_e32 v3, v3, v0
	v_cvt_pk_bf16_f32 v0, v8, v9
	v_cvt_pk_bf16_f32 v3, v6, v3
	global_store_dwordx4 v[4:5], v[0:3], off
	s_cbranch_vccz .LBB0_210
	s_waitcnt vmcnt(0)
	s_cmpk_gt_u32 s24, 0xff
	s_cbranch_scc1 .LBB0_217
	s_barrier

; #define PG8_STAGE(bufoff, gbase, voff) do { _Pragma("unroll") for (int _i = 0; _i < 2; ++_i) \
;         __builtin_amdgcn_global_load_lds((const unsigned*)((const char*)(gbase) + (voff)[_i]), (LAS unsigned*)(lds + (bufoff) + ldsw + _i * 8192), 16, 0, 0); } while (0)
; #define PG8_LDA(dst, b, h) do { _Pragma("unroll") for (int m = 0; m < 4; ++m) _Pragma("unroll") for (int k = 0; k < 2; ++k) dst[m][k] = *(const LAS bf16x8*)(lds + PG8_SA(b, h) + aoff + m * 2048 + k * 1024); } while (0)
; #define PG8_LDB(dst, b, h) do { _Pragma("unroll") for (int n = 0; n < 2; ++n) _Pragma("unroll") for (int k = 0; k < 2; ++k) dst[n][k] = *(const LAS bf16x8*)(lds + PG8_SB(b, h) + boff + n * 2048 + k * 1024); } while (0)
; #define PG8_MMA(ai, bj, At, Bt) do { __builtin_amdgcn_s_setprio(1); _Pragma("unroll") for (int m = 0; m < 4; ++m) _Pragma("unroll") for (int n = 0; n < 2; ++n) _Pragma("unroll") for (int k = 0; k < 2; ++k) \
;         acc[ai][bj][m][n] = __builtin_amdgcn_mfma_f32_16x16x32_bf16(Bt[n][k], At[m][k], acc[ai][bj][m][n], 0, 0, 0); __builtin_amdgcn_s_setprio(0); } while (0)
; #define PG8_WAIT_V(n) asm volatile("s_waitcnt vmcnt(" #n ")" ::: "memory")
; #define PG8_WAIT_L(n) asm volatile("s_waitcnt lgkmcnt(" #n ")" ::: "memory")
; #define PG8_BAR __builtin_amdgcn_s_barrier()
; #define PG8_SCHED __builtin_amdgcn_sched_barrier(0)
; template <class Epi, class Sched>
; __device__ __forceinline__ void gemm_phase(LAS unsigned char* lds, const Gemm g, const Sched& S, const Epi& E) {
;     ...
;             PG8_LDB(B0, 0, 0); PG8_SCHED; PG8_LDA(At, 0, 0); PG8_STAGE(PG8_SA(1, 1), a1 + hstep, voffA);
;             PG8_WAIT_L(8); PG8_BAR; PG8_WAIT_L(0); PG8_MMA(0, 0, At, B0); PG8_BAR; PG8_SCHED;
;             PG8_LDB(B1, 0, 1); PG8_STAGE(PG8_SB(0, 0), b2, voffB);
;             PG8_BAR; PG8_WAIT_L(0); PG8_MMA(0, 1, At, B1); PG8_BAR;
;             PG8_LDA(At, 0, 1); PG8_STAGE(PG8_SA(0, 0), a2, voffA);
;             PG8_BAR; PG8_WAIT_L(0); PG8_MMA(1, 0, At, B0); PG8_BAR; PG8_SCHED;
;             PG8_STAGE(PG8_SB(0, 1), b2 + hstep, voffB);
;             PG8_WAIT_V(6); PG8_BAR; PG8_MMA(1, 1, At, B1); PG8_BAR;
.LBB0_267:
	s_add_i32 s47, s22, 2
	s_add_u32 s20, s16, 0x100
	s_addc_u32 s21, s17, 0
	s_add_i32 s48, 0, 0x10000
	ds_read_b128 v[128:131], v161
	ds_read_b128 v[132:135], v161 offset:1024
	ds_read_b128 v[136:139], v161 offset:2048
	ds_read_b128 v[140:143], v161 offset:3072
	s_cmp_eq_u32 s11, s22
	s_cselect_b32 s22, s4, s13
	s_cselect_b32 s25, s7, s21
	s_cselect_b32 s24, s6, s20
	s_cselect_b32 s23, s5, s15
	s_add_i32 m0, s33, 0xc000
	ds_read_b128 v[144:147], v203
	ds_read_b128 v[166:169], v203 offset:1024
	ds_read_b128 v[170:173], v203 offset:2048
	ds_read_b128 v[174:177], v203 offset:3072
	ds_read_b128 v[204:207], v203 offset:4096
	ds_read_b128 v[208:211], v203 offset:5120
	ds_read_b128 v[212:215], v203 offset:6144
	ds_read_b128 v[216:219], v203 offset:7168
	global_load_lds_dwordx4 v162, s[16:17]
	s_add_i32 m0, s33, 0xe000
	s_nop 0
	global_load_lds_dwordx4 v164, s[16:17]
	s_waitcnt lgkmcnt(8)
	s_barrier
	s_waitcnt lgkmcnt(0)
	v_mfma_f32_16x16x32_bf16 v[124:127], v[128:131], v[144:147], v[124:127]
	v_mfma_f32_16x16x32_bf16 v[120:123], v[136:139], v[144:147], v[120:123]
	v_mfma_f32_16x16x32_bf16 v[116:119], v[128:131], v[170:173], v[116:119]
	v_mfma_f32_16x16x32_bf16 v[112:115], v[136:139], v[170:173], v[112:115]
	v_mfma_f32_16x16x32_bf16 v[100:103], v[128:131], v[204:207], v[100:103]
	v_mfma_f32_16x16x32_bf16 v[96:99], v[136:139], v[204:207], v[96:99]
	v_mfma_f32_16x16x32_bf16 v[84:87], v[128:131], v[212:215], v[84:87]
	v_mfma_f32_16x16x32_bf16 v[80:83], v[136:139], v[212:215], v[80:83]
	v_mfma_f32_16x16x32_bf16 v[124:127], v[132:135], v[166:169], v[124:127]
	v_mfma_f32_16x16x32_bf16 v[120:123], v[140:143], v[166:169], v[120:123]
	v_mfma_f32_16x16x32_bf16 v[116:119], v[132:135], v[174:177], v[116:119]
	v_mfma_f32_16x16x32_bf16 v[112:115], v[140:143], v[174:177], v[112:115]
	v_mfma_f32_16x16x32_bf16 v[100:103], v[132:135], v[208:211], v[100:103]
	v_mfma_f32_16x16x32_bf16 v[96:99], v[140:143], v[208:211], v[96:99]
	v_mfma_f32_16x16x32_bf16 v[84:87], v[132:135], v[216:219], v[84:87]
	v_mfma_f32_16x16x32_bf16 v[80:83], v[140:143], v[216:219], v[80:83]
	s_barrier
	s_add_i32 s49, 0, 0x14000
	s_add_i32 s16, s48, s31
	ds_read_b128 v[220:223], v161 offset:16384
	ds_read_b128 v[224:227], v161 offset:17408
	ds_read_b128 v[228:231], v161 offset:18432
	ds_read_b128 v[232:235], v161 offset:19456
	s_add_u32 s84, s22, 0x80
	s_addc_u32 s85, s23, 0
	s_mov_b32 m0, s16
	s_nop 0
	global_load_lds_dwordx4 v148, s[22:23]
	s_add_i32 m0, s16, 0x2000
	s_nop 0
	global_load_lds_dwordx4 v160, s[22:23]
	s_barrier
	s_waitcnt lgkmcnt(0)
	v_mfma_f32_16x16x32_bf16 v[108:111], v[220:223], v[144:147], v[108:111]
	v_mfma_f32_16x16x32_bf16 v[104:107], v[228:231], v[144:147], v[104:107]
	v_mfma_f32_16x16x32_bf16 v[92:95], v[220:223], v[170:173], v[92:95]
	v_mfma_f32_16x16x32_bf16 v[88:91], v[228:231], v[170:173], v[88:91]
	v_mfma_f32_16x16x32_bf16 v[76:79], v[220:223], v[204:207], v[76:79]
	v_mfma_f32_16x16x32_bf16 v[72:75], v[228:231], v[204:207], v[72:75]
	v_mfma_f32_16x16x32_bf16 v[68:71], v[220:223], v[212:215], v[68:71]
	v_mfma_f32_16x16x32_bf16 v[64:67], v[228:231], v[212:215], v[64:67]
	v_mfma_f32_16x16x32_bf16 v[108:111], v[224:227], v[166:169], v[108:111]
	v_mfma_f32_16x16x32_bf16 v[104:107], v[232:235], v[166:169], v[104:107]
	v_mfma_f32_16x16x32_bf16 v[92:95], v[224:227], v[174:177], v[92:95]
	v_mfma_f32_16x16x32_bf16 v[88:91], v[232:235], v[174:177], v[88:91]
	v_mfma_f32_16x16x32_bf16 v[76:79], v[224:227], v[208:211], v[76:79]
	v_mfma_f32_16x16x32_bf16 v[72:75], v[232:235], v[208:211], v[72:75]
	v_mfma_f32_16x16x32_bf16 v[68:71], v[224:227], v[216:219], v[68:71]
	v_mfma_f32_16x16x32_bf16 v[64:67], v[232:235], v[216:219], v[64:67]
	s_mov_b32 m0, s33
	s_add_u32 s86, s24, 0x80
	s_addc_u32 s87, s25, 0
	s_barrier
	ds_read_b128 v[144:147], v203 offset:16384
	ds_read_b128 v[166:169], v203 offset:17408
	ds_read_b128 v[170:173], v203 offset:18432
	ds_read_b128 v[174:177], v203 offset:19456
	ds_read_b128 v[204:207], v203 offset:20480
	ds_read_b128 v[208:211], v203 offset:21504
	ds_read_b128 v[212:215], v203 offset:22528
	ds_read_b128 v[216:219], v203 offset:23552
	global_load_lds_dwordx4 v148, s[24:25]
	s_mov_b32 m0, s34
	s_nop 0
	global_load_lds_dwordx4 v160, s[24:25]
	s_barrier
	s_waitcnt lgkmcnt(0)
	v_mfma_f32_16x16x32_bf16 v[60:63], v[128:131], v[144:147], v[60:63]
	v_mfma_f32_16x16x32_bf16 v[56:59], v[136:139], v[144:147], v[56:59]
	v_mfma_f32_16x16x32_bf16 v[52:55], v[128:131], v[170:173], v[52:55]
	v_mfma_f32_16x16x32_bf16 v[48:51], v[136:139], v[170:173], v[48:51]
	v_mfma_f32_16x16x32_bf16 v[36:39], v[128:131], v[204:207], v[36:39]
	v_mfma_f32_16x16x32_bf16 v[32:35], v[136:139], v[204:207], v[32:35]
	v_mfma_f32_16x16x32_bf16 v[20:23], v[128:131], v[212:215], v[20:23]
	v_mfma_f32_16x16x32_bf16 v[16:19], v[136:139], v[212:215], v[16:19]
	v_mfma_f32_16x16x32_bf16 v[60:63], v[132:135], v[166:169], v[60:63]
	v_mfma_f32_16x16x32_bf16 v[56:59], v[140:143], v[166:169], v[56:59]
	v_mfma_f32_16x16x32_bf16 v[52:55], v[132:135], v[174:177], v[52:55]
	v_mfma_f32_16x16x32_bf16 v[48:51], v[140:143], v[174:177], v[48:51]
	v_mfma_f32_16x16x32_bf16 v[36:39], v[132:135], v[208:211], v[36:39]
	v_mfma_f32_16x16x32_bf16 v[32:35], v[140:143], v[208:211], v[32:35]
	v_mfma_f32_16x16x32_bf16 v[20:23], v[132:135], v[216:219], v[20:23]
	v_mfma_f32_16x16x32_bf16 v[16:19], v[140:143], v[216:219], v[16:19]
	s_barrier
	s_add_u32 s16, s22, 0x80000
	s_addc_u32 s17, s23, 0
	s_add_i32 s48, s49, s31
	s_mov_b32 m0, s48
	s_nop 0
	global_load_lds_dwordx4 v148, s[16:17]
	s_add_i32 m0, s48, 0x2000
	s_nop 0
	global_load_lds_dwordx4 v160, s[16:17]
	s_waitcnt vmcnt(6)
	s_barrier
; #define PG8_STAGE(bufoff, gbase, voff) do { _Pragma("unroll") for (int _i = 0; _i < 2; ++_i) \
;         __builtin_amdgcn_global_load_lds((const unsigned*)((const char*)(gbase) + (voff)[_i]), (LAS unsigned*)(lds + (bufoff) + ldsw + _i * 8192), 16, 0, 0); } while (0)
; #define PG8_LDA(dst, b, h) do { _Pragma("unroll") for (int m = 0; m < 4; ++m) _Pragma("unroll") for (int k = 0; k < 2; ++k) dst[m][k] = *(const LAS bf16x8*)(lds + PG8_SA(b, h) + aoff + m * 2048 + k * 1024); } while (0)
; #define PG8_LDB(dst, b, h) do { _Pragma("unroll") for (int n = 0; n < 2; ++n) _Pragma("unroll") for (int k = 0; k < 2; ++k) dst[n][k] = *(const LAS bf16x8*)(lds + PG8_SB(b, h) + boff + n * 2048 + k * 1024); } while (0)
; #define PG8_MMA(ai, bj, At, Bt) do { __builtin_amdgcn_s_setprio(1); _Pragma("unroll") for (int m = 0; m < 4; ++m) _Pragma("unroll") for (int n = 0; n < 2; ++n) _Pragma("unroll") for (int k = 0; k < 2; ++k) \
;         acc[ai][bj][m][n] = __builtin_amdgcn_mfma_f32_16x16x32_bf16(Bt[n][k], At[m][k], acc[ai][bj][m][n], 0, 0, 0); __builtin_amdgcn_s_setprio(0); } while (0)
; #define PG8_WAIT_V(n) asm volatile("s_waitcnt vmcnt(" #n ")" ::: "memory")
; #define PG8_WAIT_L(n) asm volatile("s_waitcnt lgkmcnt(" #n ")" ::: "memory")
; #define PG8_BAR __builtin_amdgcn_s_barrier()
; #define PG8_SCHED __builtin_amdgcn_sched_barrier(0)
; template <class Epi, class Sched>
; __device__ __forceinline__ void gemm_phase(LAS unsigned char* lds, const Gemm g, const Sched& S, const Epi& E) {
;     ...
;             PG8_WAIT_V(6); PG8_BAR; PG8_MMA(1, 1, At, B1); PG8_BAR;
;             PG8_LDB(B0, 1, 0); PG8_SCHED; PG8_LDA(At, 1, 0); PG8_STAGE(PG8_SA(0, 1), a2 + hstep, voffA);
;             PG8_WAIT_L(8); PG8_BAR; PG8_WAIT_L(0); PG8_MMA(0, 0, At, B0); PG8_BAR; PG8_SCHED;
;             PG8_LDB(B1, 1, 1); PG8_STAGE(PG8_SB(1, 0), b3, voffB);
;             PG8_BAR; PG8_WAIT_L(0); PG8_MMA(0, 1, At, B1); PG8_BAR;
;             PG8_LDA(At, 1, 1); PG8_STAGE(PG8_SA(1, 0), a3, voffA);
;             PG8_BAR; PG8_WAIT_L(0); PG8_MMA(1, 0, At, B0); PG8_BAR; PG8_SCHED;
	v_mfma_f32_16x16x32_bf16 v[44:47], v[220:223], v[144:147], v[44:47]
	v_mfma_f32_16x16x32_bf16 v[40:43], v[228:231], v[144:147], v[40:43]
	v_mfma_f32_16x16x32_bf16 v[28:31], v[220:223], v[170:173], v[28:31]
	v_mfma_f32_16x16x32_bf16 v[24:27], v[228:231], v[170:173], v[24:27]
	v_mfma_f32_16x16x32_bf16 v[12:15], v[220:223], v[204:207], v[12:15]
	v_mfma_f32_16x16x32_bf16 v[8:11], v[228:231], v[204:207], v[8:11]
	v_mfma_f32_16x16x32_bf16 v[4:7], v[220:223], v[212:215], v[4:7]
	v_mfma_f32_16x16x32_bf16 v[0:3], v[228:231], v[212:215], v[0:3]
	v_mfma_f32_16x16x32_bf16 v[44:47], v[224:227], v[166:169], v[44:47]
	v_mfma_f32_16x16x32_bf16 v[40:43], v[232:235], v[166:169], v[40:43]
	v_mfma_f32_16x16x32_bf16 v[28:31], v[224:227], v[174:177], v[28:31]
	v_mfma_f32_16x16x32_bf16 v[24:27], v[232:235], v[174:177], v[24:27]
	v_mfma_f32_16x16x32_bf16 v[12:15], v[224:227], v[208:211], v[12:15]
	v_mfma_f32_16x16x32_bf16 v[8:11], v[232:235], v[208:211], v[8:11]
	v_mfma_f32_16x16x32_bf16 v[4:7], v[224:227], v[216:219], v[4:7]
	v_mfma_f32_16x16x32_bf16 v[0:3], v[232:235], v[216:219], v[0:3]
	s_add_i32 s48, 0, 0x18000
	s_barrier
	ds_read_b128 v[128:131], v161 offset:32768
	ds_read_b128 v[132:135], v161 offset:33792
	ds_read_b128 v[136:139], v161 offset:34816
	ds_read_b128 v[140:143], v161 offset:35840
	s_add_u32 s16, s24, 0x80000
	s_addc_u32 s17, s25, 0
	s_mov_b32 m0, s35
	ds_read_b128 v[144:147], v203 offset:32768
	ds_read_b128 v[166:169], v203 offset:33792
	ds_read_b128 v[170:173], v203 offset:34816
	ds_read_b128 v[174:177], v203 offset:35840
	ds_read_b128 v[204:207], v203 offset:36864
	ds_read_b128 v[208:211], v203 offset:37888
	ds_read_b128 v[212:215], v203 offset:38912
	ds_read_b128 v[216:219], v203 offset:39936
	global_load_lds_dwordx4 v148, s[16:17]
	s_mov_b32 m0, s36
	s_nop 0
	global_load_lds_dwordx4 v160, s[16:17]
	s_waitcnt lgkmcnt(8)
	s_barrier
	s_waitcnt lgkmcnt(0)
	v_mfma_f32_16x16x32_bf16 v[124:127], v[128:131], v[144:147], v[124:127]
	v_mfma_f32_16x16x32_bf16 v[120:123], v[136:139], v[144:147], v[120:123]
	v_mfma_f32_16x16x32_bf16 v[116:119], v[128:131], v[170:173], v[116:119]
	v_mfma_f32_16x16x32_bf16 v[112:115], v[136:139], v[170:173], v[112:115]
	v_mfma_f32_16x16x32_bf16 v[100:103], v[128:131], v[204:207], v[100:103]
	v_mfma_f32_16x16x32_bf16 v[96:99], v[136:139], v[204:207], v[96:99]
	v_mfma_f32_16x16x32_bf16 v[84:87], v[128:131], v[212:215], v[84:87]
	v_mfma_f32_16x16x32_bf16 v[80:83], v[136:139], v[212:215], v[80:83]
	v_mfma_f32_16x16x32_bf16 v[124:127], v[132:135], v[166:169], v[124:127]
	v_mfma_f32_16x16x32_bf16 v[120:123], v[140:143], v[166:169], v[120:123]
	v_mfma_f32_16x16x32_bf16 v[116:119], v[132:135], v[174:177], v[116:119]
	v_mfma_f32_16x16x32_bf16 v[112:115], v[140:143], v[174:177], v[112:115]
	v_mfma_f32_16x16x32_bf16 v[100:103], v[132:135], v[208:211], v[100:103]
	v_mfma_f32_16x16x32_bf16 v[96:99], v[140:143], v[208:211], v[96:99]
	v_mfma_f32_16x16x32_bf16 v[84:87], v[132:135], v[216:219], v[84:87]
	v_mfma_f32_16x16x32_bf16 v[80:83], v[140:143], v[216:219], v[80:83]
	s_barrier
	s_add_i32 s24, 0, 0x1c000
	s_add_i32 s16, s48, s31
	s_mov_b32 m0, s16
	ds_read_b128 v[220:223], v161 offset:49152
	ds_read_b128 v[224:227], v161 offset:50176
	ds_read_b128 v[228:231], v161 offset:51200
	ds_read_b128 v[232:235], v161 offset:52224
	global_load_lds_dwordx4 v148, s[84:85]
	s_add_i32 m0, s16, 0x2000
	s_nop 0
	global_load_lds_dwordx4 v160, s[84:85]
	s_barrier
	s_waitcnt lgkmcnt(0)
	v_mfma_f32_16x16x32_bf16 v[108:111], v[220:223], v[144:147], v[108:111]
	v_mfma_f32_16x16x32_bf16 v[104:107], v[228:231], v[144:147], v[104:107]
	v_mfma_f32_16x16x32_bf16 v[92:95], v[220:223], v[170:173], v[92:95]
	v_mfma_f32_16x16x32_bf16 v[88:91], v[228:231], v[170:173], v[88:91]
	v_mfma_f32_16x16x32_bf16 v[76:79], v[220:223], v[204:207], v[76:79]
	v_mfma_f32_16x16x32_bf16 v[72:75], v[228:231], v[204:207], v[72:75]
	v_mfma_f32_16x16x32_bf16 v[68:71], v[220:223], v[212:215], v[68:71]
	v_mfma_f32_16x16x32_bf16 v[64:67], v[228:231], v[212:215], v[64:67]
	v_mfma_f32_16x16x32_bf16 v[108:111], v[224:227], v[166:169], v[108:111]
	v_mfma_f32_16x16x32_bf16 v[104:107], v[232:235], v[166:169], v[104:107]
	v_mfma_f32_16x16x32_bf16 v[92:95], v[224:227], v[174:177], v[92:95]
	v_mfma_f32_16x16x32_bf16 v[88:91], v[232:235], v[174:177], v[88:91]
	v_mfma_f32_16x16x32_bf16 v[76:79], v[224:227], v[208:211], v[76:79]
	v_mfma_f32_16x16x32_bf16 v[72:75], v[232:235], v[208:211], v[72:75]
	v_mfma_f32_16x16x32_bf16 v[68:71], v[224:227], v[216:219], v[68:71]
	v_mfma_f32_16x16x32_bf16 v[64:67], v[232:235], v[216:219], v[64:67]
	s_mov_b32 m0, s39
	s_barrier
	ds_read_b128 v[144:147], v203 offset:49152
	ds_read_b128 v[166:169], v203 offset:50176
	ds_read_b128 v[170:173], v203 offset:51200
	ds_read_b128 v[174:177], v203 offset:52224
	ds_read_b128 v[204:207], v203 offset:53248
	ds_read_b128 v[208:211], v203 offset:54272
	ds_read_b128 v[212:215], v203 offset:55296
	ds_read_b128 v[216:219], v203 offset:56320
	global_load_lds_dwordx4 v148, s[86:87]
	s_mov_b32 m0, s40
	s_nop 0
	global_load_lds_dwordx4 v160, s[86:87]
	s_barrier
	s_waitcnt lgkmcnt(0)
	v_mfma_f32_16x16x32_bf16 v[60:63], v[128:131], v[144:147], v[60:63]
	v_mfma_f32_16x16x32_bf16 v[56:59], v[136:139], v[144:147], v[56:59]
	v_mfma_f32_16x16x32_bf16 v[52:55], v[128:131], v[170:173], v[52:55]
	v_mfma_f32_16x16x32_bf16 v[48:51], v[136:139], v[170:173], v[48:51]
	v_mfma_f32_16x16x32_bf16 v[36:39], v[128:131], v[204:207], v[36:39]
	v_mfma_f32_16x16x32_bf16 v[32:35], v[136:139], v[204:207], v[32:35]
	v_mfma_f32_16x16x32_bf16 v[20:23], v[128:131], v[212:215], v[20:23]
	v_mfma_f32_16x16x32_bf16 v[16:19], v[136:139], v[212:215], v[16:19]
	v_mfma_f32_16x16x32_bf16 v[60:63], v[132:135], v[166:169], v[60:63]
	v_mfma_f32_16x16x32_bf16 v[56:59], v[140:143], v[166:169], v[56:59]
	v_mfma_f32_16x16x32_bf16 v[52:55], v[132:135], v[174:177], v[52:55]
	v_mfma_f32_16x16x32_bf16 v[48:51], v[140:143], v[174:177], v[48:51]
	v_mfma_f32_16x16x32_bf16 v[36:39], v[132:135], v[208:211], v[36:39]
	v_mfma_f32_16x16x32_bf16 v[32:35], v[140:143], v[208:211], v[32:35]
	v_mfma_f32_16x16x32_bf16 v[20:23], v[132:135], v[216:219], v[20:23]
	v_mfma_f32_16x16x32_bf16 v[16:19], v[140:143], v[216:219], v[16:19]
	s_barrier
; #define PG8_STAGE(bufoff, gbase, voff) do { _Pragma("unroll") for (int _i = 0; _i < 2; ++_i) \
;         __builtin_amdgcn_global_load_lds((const unsigned*)((const char*)(gbase) + (voff)[_i]), (LAS unsigned*)(lds + (bufoff) + ldsw + _i * 8192), 16, 0, 0); } while (0)
; #define PG8_MMA(ai, bj, At, Bt) do { __builtin_amdgcn_s_setprio(1); _Pragma("unroll") for (int m = 0; m < 4; ++m) _Pragma("unroll") for (int n = 0; n < 2; ++n) _Pragma("unroll") for (int k = 0; k < 2; ++k) \
;         acc[ai][bj][m][n] = __builtin_amdgcn_mfma_f32_16x16x32_bf16(Bt[n][k], At[m][k], acc[ai][bj][m][n], 0, 0, 0); __builtin_amdgcn_s_setprio(0); } while (0)
; #define PG8_WAIT_V(n) asm volatile("s_waitcnt vmcnt(" #n ")" ::: "memory")
; #define PG8_WAIT_L(n) asm volatile("s_waitcnt lgkmcnt(" #n ")" ::: "memory")
; #define PG8_BAR __builtin_amdgcn_s_barrier()
; #define PG8_SCHED __builtin_amdgcn_sched_barrier(0)
;     __device__ __forceinline__ void operator()(const f32x4 (&acc)[2][2][4][2], const Unit& u, int wr, int wc, int fr, int fq) const {
;     ...
;         const float* base = (u.pm < 32) ? base_lo : base_hi;
; #pragma unroll
;         for (int ai = 0; ai < 2; ++ai) {
;             f32x4 bs[4][2][2];
; #pragma unroll
;             for (int m = 0; m < 4; ++m) { const size_t off = (size_t)(row0 + ai * HALF + m * 16) * DM + col0;
; #pragma unroll
;                 for (int bj = 0; bj < 2; ++bj)
; #pragma unroll
;                     for (int n = 0; n < 2; ++n) bs[m][bj][n] = *(const f32x4*)(base + off + bj * HALF + n * 16); }
; #pragma unroll
;             for (int m = 0; m < 4; ++m) { const size_t off = (size_t)(row0 + ai * HALF + m * 16) * DM + col0;
; #pragma unroll
;                 for (int bj = 0; bj < 2; ++bj)
; #pragma unroll
;                     for (int n = 0; n < 2; ++n) *(f32x4*)(out + off + bj * HALF + n * 16) = bs[m][bj][n] + scale * acc[ai][bj][m][n]; }
;             asm volatile("" ::: "memory");
; template <class Epi, class Sched>
; __device__ __forceinline__ void gemm_phase(LAS unsigned char* lds, const Gemm g, const Sched& S, const Epi& E) {
;     ...
;             PG8_BAR; PG8_WAIT_L(0); PG8_MMA(1, 0, At, B0); PG8_BAR; PG8_SCHED;
;             PG8_STAGE(PG8_SB(1, 1), b3 + hstep, voffB);
;             PG8_WAIT_V(6); PG8_BAR; PG8_MMA(1, 1, At, B1); PG8_BAR;
	s_add_u32 s16, s22, 0x80080
	s_addc_u32 s17, s23, 0
	s_add_i32 s22, s24, s31
	s_mov_b32 m0, s22
	s_nop 0
	global_load_lds_dwordx4 v148, s[16:17]
	s_add_i32 m0, s22, 0x2000
	s_nop 0
	global_load_lds_dwordx4 v160, s[16:17]
	s_waitcnt vmcnt(6)
	s_barrier
	v_mfma_f32_16x16x32_bf16 v[44:47], v[220:223], v[144:147], v[44:47]
	v_mfma_f32_16x16x32_bf16 v[40:43], v[228:231], v[144:147], v[40:43]
	v_mfma_f32_16x16x32_bf16 v[28:31], v[220:223], v[170:173], v[28:31]
	v_mfma_f32_16x16x32_bf16 v[24:27], v[228:231], v[170:173], v[24:27]
	v_mfma_f32_16x16x32_bf16 v[12:15], v[220:223], v[204:207], v[12:15]
	v_mfma_f32_16x16x32_bf16 v[8:11], v[228:231], v[204:207], v[8:11]
	v_mfma_f32_16x16x32_bf16 v[4:7], v[220:223], v[212:215], v[4:7]
	v_mfma_f32_16x16x32_bf16 v[0:3], v[228:231], v[212:215], v[0:3]
	v_mfma_f32_16x16x32_bf16 v[44:47], v[224:227], v[166:169], v[44:47]
	v_mfma_f32_16x16x32_bf16 v[40:43], v[232:235], v[166:169], v[40:43]
	v_mfma_f32_16x16x32_bf16 v[28:31], v[224:227], v[174:177], v[28:31]
	v_mfma_f32_16x16x32_bf16 v[24:27], v[232:235], v[174:177], v[24:27]
	v_mfma_f32_16x16x32_bf16 v[12:15], v[224:227], v[208:211], v[12:15]
	v_mfma_f32_16x16x32_bf16 v[8:11], v[232:235], v[208:211], v[8:11]
	v_mfma_f32_16x16x32_bf16 v[4:7], v[224:227], v[216:219], v[4:7]
	v_mfma_f32_16x16x32_bf16 v[0:3], v[232:235], v[216:219], v[0:3]
	s_add_u32 s13, s13, 0x100
	s_addc_u32 s15, s15, 0
	s_cmp_ge_i32 s47, s45
	s_mov_b64 s[16:17], s[20:21]
	s_mov_b32 s22, s47
	s_barrier
	s_cbranch_scc0 .LBB0_267
	v_lshl_add_u32 v166, s46, 8, v200
	v_lshl_or_b32 v168, s44, 8, v202
	s_mov_b64 s[16:17], -1
	s_cmp_lt_i32 s82, 0
	v_ashrrev_i32_e32 v169, 31, v168
	v_ashrrev_i32_e32 v167, 31, v166
	s_cbranch_scc0 .LBB0_270
	v_lshlrev_b64 v[170:171], 2, v[168:169]
	v_lshl_add_u64 v[172:173], s[60:61], 0, v[170:171]
	v_lshlrev_b64 v[174:175], 13, v[166:167]
	v_lshl_add_u64 v[128:129], v[172:173], 0, v[174:175]
	global_load_dwordx4 v[204:207], v[128:129], off
	global_load_dwordx4 v[208:211], v[128:129], off offset:64
	global_load_dwordx4 v[212:215], v[128:129], off offset:512
	global_load_dwordx4 v[216:219], v[128:129], off offset:576
	v_or_b32_e32 v128, 16, v166
	v_ashrrev_i32_e32 v129, 31, v128
	v_lshlrev_b64 v[188:189], 13, v[128:129]
	v_lshl_add_u64 v[128:129], v[172:173], 0, v[188:189]
	global_load_dwordx4 v[220:223], v[128:129], off
	global_load_dwordx4 v[224:227], v[128:129], off offset:64
	global_load_dwordx4 v[228:231], v[128:129], off offset:512
	global_load_dwordx4 v[232:235], v[128:129], off offset:576
	v_or_b32_e32 v128, 32, v166
	v_ashrrev_i32_e32 v129, 31, v128
	v_lshlrev_b64 v[190:191], 13, v[128:129]
	v_lshl_add_u64 v[128:129], v[172:173], 0, v[190:191]
	global_load_dwordx4 v[236:239], v[128:129], off
	global_load_dwordx4 v[240:243], v[128:129], off offset:64
	global_load_dwordx4 v[144:147], v[128:129], off offset:512
	global_load_dwordx4 v[140:143], v[128:129], off offset:576
	v_or_b32_e32 v128, 48, v166
	v_ashrrev_i32_e32 v129, 31, v128
	v_lshlrev_b64 v[176:177], 13, v[128:129]
	v_lshl_add_u64 v[128:129], v[172:173], 0, v[176:177]
	global_load_dwordx4 v[244:247], v[128:129], off
	global_load_dwordx4 v[136:139], v[128:129], off offset:64
	global_load_dwordx4 v[132:135], v[128:129], off offset:512
	s_nop 0
	global_load_dwordx4 v[128:131], v[128:129], off offset:576
	v_lshl_add_u64 v[248:249], s[60:61], 0, v[174:175]
	v_lshl_add_u64 v[248:249], v[248:249], 0, v[170:171]
	v_lshl_add_u64 v[188:189], s[60:61], 0, v[188:189]
	v_lshl_add_u64 v[188:189], v[188:189], 0, v[170:171]
	s_mov_b64 s[16:17], 0x100000
	s_waitcnt vmcnt(0)
	v_pk_add_f32 v[206:207], v[206:207], v[126:127]
	v_pk_add_f32 v[204:205], v[204:205], v[124:125]
	global_store_dwordx4 v[248:249], v[204:207], off
	v_pk_add_f32 v[146:147], v[146:147], v[78:79]
	s_nop 0
	v_pk_add_f32 v[206:207], v[210:211], v[122:123]
	v_pk_add_f32 v[204:205], v[208:209], v[120:121]
	global_store_dwordx4 v[248:249], v[204:207], off offset:64
	v_pk_add_f32 v[144:145], v[144:145], v[76:77]
	v_pk_add_f32 v[142:143], v[142:143], v[74:75]
	v_pk_add_f32 v[206:207], v[214:215], v[110:111]
	v_pk_add_f32 v[204:205], v[212:213], v[108:109]
	global_store_dwordx4 v[248:249], v[204:207], off offset:512
	v_pk_add_f32 v[140:141], v[140:141], v[72:73]
	v_pk_add_f32 v[138:139], v[138:139], v[82:83]
	v_pk_add_f32 v[206:207], v[218:219], v[106:107]
	v_pk_add_f32 v[204:205], v[216:217], v[104:105]
	global_store_dwordx4 v[248:249], v[204:207], off offset:576
	v_pk_add_f32 v[136:137], v[136:137], v[80:81]
	v_pk_add_f32 v[134:135], v[134:135], v[70:71]
	v_pk_add_f32 v[206:207], v[222:223], v[118:119]
	v_pk_add_f32 v[204:205], v[220:221], v[116:117]
	global_store_dwordx4 v[188:189], v[204:207], off
	v_pk_add_f32 v[132:133], v[132:133], v[68:69]
	v_pk_add_f32 v[130:131], v[130:131], v[66:67]
	v_pk_add_f32 v[206:207], v[226:227], v[114:115]
	v_pk_add_f32 v[204:205], v[224:225], v[112:113]
	global_store_dwordx4 v[188:189], v[204:207], off offset:64
	v_pk_add_f32 v[128:129], v[128:129], v[64:65]
	s_nop 0
	v_pk_add_f32 v[206:207], v[230:231], v[94:95]
	v_pk_add_f32 v[204:205], v[228:229], v[92:93]
	global_store_dwordx4 v[188:189], v[204:207], off offset:512
	s_nop 1
	v_pk_add_f32 v[206:207], v[234:235], v[90:91]
	v_pk_add_f32 v[204:205], v[232:233], v[88:89]
	global_store_dwordx4 v[188:189], v[204:207], off offset:576
;     __device__ __forceinline__ void operator()(const f32x4 (&acc)[2][2][4][2], const Unit& u, int wr, int wc, int fr, int fq) const {
;     ...
;         const float* base = (u.pm < 32) ? base_lo : base_hi;
; #pragma unroll
;         for (int ai = 0; ai < 2; ++ai) {
;             f32x4 bs[4][2][2];
; #pragma unroll
;             for (int m = 0; m < 4; ++m) { const size_t off = (size_t)(row0 + ai * HALF + m * 16) * DM + col0;
; #pragma unroll
;                 for (int bj = 0; bj < 2; ++bj)
; #pragma unroll
;                     for (int n = 0; n < 2; ++n) bs[m][bj][n] = *(const f32x4*)(base + off + bj * HALF + n * 16); }
; #pragma unroll
;             for (int m = 0; m < 4; ++m) { const size_t off = (size_t)(row0 + ai * HALF + m * 16) * DM + col0;
; #pragma unroll
;                 for (int bj = 0; bj < 2; ++bj)
; #pragma unroll
;                     for (int n = 0; n < 2; ++n) *(f32x4*)(out + off + bj * HALF + n * 16) = bs[m][bj][n] + scale * acc[ai][bj][m][n]; }
;             asm volatile("" ::: "memory");
	v_lshl_add_u64 v[188:189], s[60:61], 0, v[190:191]
	v_lshl_add_u64 v[188:189], v[188:189], 0, v[170:171]
	v_pk_add_f32 v[206:207], v[238:239], v[102:103]
	v_pk_add_f32 v[204:205], v[236:237], v[100:101]
	global_store_dwordx4 v[188:189], v[144:147], off offset:512
	global_store_dwordx4 v[188:189], v[204:207], off
	global_store_dwordx4 v[188:189], v[140:143], off offset:576
	v_lshl_add_u64 v[144:145], s[60:61], 0, v[176:177]
	v_pk_add_f32 v[206:207], v[242:243], v[98:99]
	v_pk_add_f32 v[204:205], v[240:241], v[96:97]
	v_pk_add_f32 v[142:143], v[246:247], v[86:87]
	v_pk_add_f32 v[140:141], v[244:245], v[84:85]
	v_lshl_add_u64 v[144:145], v[144:145], 0, v[170:171]
	global_store_dwordx4 v[188:189], v[204:207], off offset:64
	global_store_dwordx4 v[144:145], v[140:143], off
	global_store_dwordx4 v[144:145], v[136:139], off offset:64
	global_store_dwordx4 v[144:145], v[132:135], off offset:512
	global_store_dwordx4 v[144:145], v[128:131], off offset:576
	v_lshl_add_u64 v[146:147], v[174:175], 0, s[16:17]
	s_mov_b64 s[16:17], 0x120000
	v_lshl_add_u64 v[128:129], v[172:173], 0, v[146:147]
	global_load_dwordx4 v[142:145], v[128:129], off
	global_load_dwordx4 v[204:207], v[128:129], off offset:64
	global_load_dwordx4 v[208:211], v[128:129], off offset:512
	global_load_dwordx4 v[212:215], v[128:129], off offset:576
	v_lshl_add_u64 v[176:177], v[174:175], 0, s[16:17]
	v_lshl_add_u64 v[128:129], v[172:173], 0, v[176:177]
	global_load_dwordx4 v[216:219], v[128:129], off
	global_load_dwordx4 v[220:223], v[128:129], off offset:64
	global_load_dwordx4 v[224:227], v[128:129], off offset:512
	global_load_dwordx4 v[228:231], v[128:129], off offset:576
	s_mov_b64 s[16:17], 0x140000
	v_lshl_add_u64 v[188:189], v[174:175], 0, s[16:17]
	s_mov_b64 s[16:17], 0x160000
	v_lshl_add_u64 v[128:129], v[172:173], 0, v[188:189]
	v_lshl_add_u64 v[140:141], v[174:175], 0, s[16:17]
	global_load_dwordx4 v[232:235], v[128:129], off
	global_load_dwordx4 v[236:239], v[128:129], off offset:64
	global_load_dwordx4 v[240:243], v[128:129], off offset:512
	global_load_dwordx4 v[244:247], v[128:129], off offset:576
	v_lshl_add_u64 v[128:129], v[172:173], 0, v[140:141]
	global_load_dwordx4 v[172:175], v[128:129], off
	global_load_dwordx4 v[136:139], v[128:129], off offset:64
	global_load_dwordx4 v[132:135], v[128:129], off offset:512
	s_nop 0
	global_load_dwordx4 v[128:131], v[128:129], off offset:576
	v_lshl_add_u64 v[146:147], s[60:61], 0, v[146:147]
	v_lshl_add_u64 v[146:147], v[146:147], 0, v[170:171]
	v_lshl_add_u64 v[140:141], s[60:61], 0, v[140:141]
	v_lshl_add_u64 v[140:141], v[140:141], 0, v[170:171]
	s_mov_b64 s[16:17], 0
	s_waitcnt vmcnt(0)
	v_pk_add_f32 v[144:145], v[62:63], v[144:145]
	v_pk_add_f32 v[142:143], v[60:61], v[142:143]
	global_store_dwordx4 v[146:147], v[142:145], off
	v_pk_add_f32 v[138:139], v[18:19], v[138:139]
	s_nop 0
	v_pk_add_f32 v[144:145], v[58:59], v[206:207]
	v_pk_add_f32 v[142:143], v[56:57], v[204:205]
	global_store_dwordx4 v[146:147], v[142:145], off offset:64
	v_pk_add_f32 v[136:137], v[16:17], v[136:137]
	v_pk_add_f32 v[134:135], v[6:7], v[134:135]
	v_pk_add_f32 v[144:145], v[46:47], v[210:211]
	v_pk_add_f32 v[142:143], v[44:45], v[208:209]
	global_store_dwordx4 v[146:147], v[142:145], off offset:512
	v_pk_add_f32 v[132:133], v[4:5], v[132:133]
	v_pk_add_f32 v[130:131], v[2:3], v[130:131]
	v_pk_add_f32 v[144:145], v[42:43], v[214:215]
	v_pk_add_f32 v[142:143], v[40:41], v[212:213]
	global_store_dwordx4 v[146:147], v[142:145], off offset:576
	v_lshl_add_u64 v[146:147], s[60:61], 0, v[176:177]
	v_lshl_add_u64 v[146:147], v[146:147], 0, v[170:171]
	v_pk_add_f32 v[144:145], v[54:55], v[218:219]
	v_pk_add_f32 v[142:143], v[52:53], v[216:217]
	global_store_dwordx4 v[146:147], v[142:145], off
	v_pk_add_f32 v[128:129], v[0:1], v[128:129]
	global_store_dwordx4 v[140:141], v[136:139], off offset:64
	v_pk_add_f32 v[144:145], v[50:51], v[222:223]
	v_pk_add_f32 v[142:143], v[48:49], v[220:221]
	global_store_dwordx4 v[146:147], v[142:145], off offset:64
	global_store_dwordx4 v[140:141], v[132:135], off offset:512
	global_store_dwordx4 v[140:141], v[128:131], off offset:576
	v_pk_add_f32 v[144:145], v[30:31], v[226:227]
	v_pk_add_f32 v[142:143], v[28:29], v[224:225]
	global_store_dwordx4 v[146:147], v[142:145], off offset:512
	s_nop 1
	v_pk_add_f32 v[144:145], v[26:27], v[230:231]
	v_pk_add_f32 v[142:143], v[24:25], v[228:229]
	global_store_dwordx4 v[146:147], v[142:145], off offset:576
	v_lshl_add_u64 v[146:147], s[60:61], 0, v[188:189]
	v_lshl_add_u64 v[146:147], v[146:147], 0, v[170:171]
	v_pk_add_f32 v[144:145], v[38:39], v[234:235]
	v_pk_add_f32 v[142:143], v[36:37], v[232:233]
	global_store_dwordx4 v[146:147], v[142:145], off
	s_nop 1
	v_pk_add_f32 v[144:145], v[34:35], v[238:239]
	v_pk_add_f32 v[142:143], v[32:33], v[236:237]
	global_store_dwordx4 v[146:147], v[142:145], off offset:64
	s_nop 1
	v_pk_add_f32 v[144:145], v[14:15], v[242:243]
	v_pk_add_f32 v[142:143], v[12:13], v[240:241]
	global_store_dwordx4 v[146:147], v[142:145], off offset:512
	s_nop 1
	v_pk_add_f32 v[144:145], v[10:11], v[246:247]
	v_pk_add_f32 v[142:143], v[8:9], v[244:245]
	global_store_dwordx4 v[146:147], v[142:145], off offset:576
	s_nop 1
	v_pk_add_f32 v[144:145], v[22:23], v[174:175]
	v_pk_add_f32 v[142:143], v[20:21], v[172:173]
	global_store_dwordx4 v[140:141], v[142:145], off
